# mixer-B main loop hand-rescheduled: ping-pong register regions, softmax VALU in PV/QK MFMA shadow, V-frag prefetch
# speedup vs baseline: 1.0039x; 1.0039x over previous
; #define LAS __attribute__((address_space(3)))
; __device__ __forceinline__ float half_max(float v) { auto rr = __builtin_amdgcn_permlane32_swap(__float_as_uint(v), __float_as_uint(v), false, false); return fmaxf(__uint_as_float(rr[0]), __uint_as_float(rr[1])); }
; #define SLOAD(i, k0) do { sr_[i].vs0 = *(const bf16x8*)(Vh + (size_t)((k0) + sr) * PW + sc); sr_[i].vs1 = *(const bf16x8*)(Vh + (size_t)((k0) + 32 + sr) * PW + sc); \
;     sr_[i].ks0 = *(const bf16x8*)(Kh + (size_t)((k0) + sr) * PW + sc); sr_[i].ks1 = *(const bf16x8*)(Kh + (size_t)((k0) + 32 + sr) * PW + sc); } while (0)
; __device__ __forceinline__ void partialSM(f32x16& p0, f32x16& p1, const LAS float* tbp, int relc, float cL, float cR, float& m_reg, float& mn, float& alpha) {
;     float cb = 0.f;
;     if (relc + 63 <= -559) cb = cL;
;     else if (relc - 31 >= 559) cb = cR;
;     else {
; #pragma unroll
;         for (int r = 0; r < 16; ++r) { p0[r] += tbp[(r & 3) + 8 * (r >> 2)]; p1[r] += tbp[32 + (r & 3) + 8 * (r >> 2)]; }
;     }
;     float pmax = p0[0];
; #pragma unroll
;     for (int r = 1; r < 16; ++r) pmax = fmaxf(pmax, p0[r]);
; #pragma unroll
;     for (int r = 0; r < 16; ++r) pmax = fmaxf(pmax, p1[r]);
;     pmax = half_max(pmax) + cb;
;     if (__builtin_expect(__all(pmax - m_reg <= 8.f), 1)) { mn = m_reg; alpha = 1.f; }
;     else { mn = fmaxf(m_reg, pmax); alpha = __builtin_amdgcn_exp2f(m_reg - mn); m_reg = mn; }
;     const float sh = mn - cb;
; #pragma unroll
;     for (int r = 0; r < 16; ++r) { p0[r] -= sh; p1[r] -= sh; }
; #pragma unroll
;     for (int r = 0; r < 16; ++r) p0[r] = __builtin_amdgcn_exp2f(p0[r]);
; }
; __device__ __forceinline__ void finishSM(f32x16& p0, f32x16& p1, float alpha, float& l_reg, bf16x8& pa0, bf16x8& pa1, bf16x8& pa2, bf16x8& pa3) {
; #pragma unroll
;     for (int r = 0; r < 16; ++r) p1[r] = __builtin_amdgcn_exp2f(p1[r]);
; __device__ __forceinline__ void unit(LAS unsigned char* lds, const bf16* __restrict__ PROJ, bf16* __restrict__ MIXED, const float* __restrict__ subln_g, float lam, int R0, int seq, int h, int qb) {
;     ...
;     SLOAD(SE, 0); asm volatile("s_waitcnt vmcnt(0)" ::: "memory"); SWRITE(0, SE); __syncthreads();
;     qkt(pA0, pA1, K_lds, qr, r32, cb0); partialSM(pA0, pA1, tbq, rc0, cL, cR, m_reg, mnA, alA);
;     SLOAD(SO, 64); if (2 < NT) SLOAD(SE, 128);
;     SWAIT(); SWRITE(1, SO); __syncthreads();
.LBB0_259:
	v_add_co_u32_e32 v38, vcc, s54, v32
	s_nop 6
	v_max_f32_e32 v58, v1, v1
	v_addc_co_u32_e32 v39, vcc, 0, v33, vcc
	v_add_co_u32_e32 v42, vcc, s55, v32
	v_max_f32_e32 v59, v0, v0
	s_nop 0
	v_addc_co_u32_e32 v43, vcc, 0, v33, vcc
	v_add_co_u32_e32 v46, vcc, s54, v34
	global_load_dwordx4 v[38:41], v[38:39], off
	s_nop 0
	global_load_dwordx4 v[42:45], v[42:43], off
	v_addc_co_u32_e32 v47, vcc, 0, v35, vcc
	v_add_co_u32_e32 v50, vcc, s55, v34
	v_max_f32_e32 v58, v59, v58
	s_nop 0
	v_addc_co_u32_e32 v51, vcc, 0, v35, vcc
	v_add_co_u32_e32 v54, vcc, s56, v34
	global_load_dwordx4 v[46:49], v[46:47], off
	s_nop 0
	global_load_dwordx4 v[50:53], v[50:51], off
	v_addc_co_u32_e32 v55, vcc, 0, v35, vcc
	v_add_co_u32_e32 v34, vcc, s57, v34
	s_and_b32 s4, s33, 0x3fffffc0
	s_nop 0
	v_addc_co_u32_e32 v35, vcc, 0, v35, vcc
	v_add_co_u32_e32 v56, vcc, s56, v32
	s_lshl_b32 s4, s4, 2
	s_nop 0
	v_addc_co_u32_e32 v57, vcc, 0, v33, vcc
	v_add_co_u32_e32 v32, vcc, s57, v32
	s_add_i32 s4, s4, 0
	s_nop 0
	v_addc_co_u32_e32 v33, vcc, 0, v33, vcc
	global_load_dwordx4 v[116:119], v[54:55], off
	global_load_dwordx4 v[112:115], v[34:35], off
	global_load_dwordx4 v[124:127], v[56:57], off
	global_load_dwordx4 v[120:123], v[32:33], off
	v_max3_f32 v32, v58, v2, v3
	v_max3_f32 v32, v32, v4, v5
	v_max3_f32 v32, v32, v6, v7
	v_max3_f32 v32, v32, v8, v9
	v_max3_f32 v32, v32, v10, v11
	v_max3_f32 v32, v32, v12, v13
	v_max3_f32 v32, v32, v14, v15
	v_max3_f32 v32, v32, v16, v17
	v_max3_f32 v32, v32, v18, v19
	v_max3_f32 v32, v32, v20, v21
	v_max3_f32 v32, v32, v22, v23
	v_max3_f32 v32, v32, v24, v25
	v_max3_f32 v32, v32, v26, v27
	v_max3_f32 v32, v32, v28, v29
	v_max3_f32 v32, v32, v30, v31
	v_mov_b32_e32 v33, v32
	s_nop 1
	v_permlane32_swap_b32_e32 v32, v33
	v_max_f32_e32 v33, v33, v33
	v_max_f32_e32 v32, v32, v32
	v_max_f32_e32 v32, v32, v33
	v_add_f32_e32 v32, v37, v32
	v_add_f32_e32 v33, 0x7149f2ca, v32
	s_lshr_b32 s90, s96, 6
	s_add_i32 s4, s4, 0x18000
	v_cmp_ge_f32_e32 vcc, s35, v33
	s_cmp_eq_u64 vcc, exec
	v_max_f32_e32 v32, 0xf149f2ca, v32
	s_cselect_b64 vcc, -1, 0
	v_cndmask_b32_e32 v148, v32, v214, vcc
	v_sub_f32_e32 v33, v148, v37
	v_sub_f32_e32 v0, v0, v33
	v_exp_f32_e32 v145, v0
	v_sub_f32_e32 v0, v1, v33
	v_exp_f32_e32 v158, v0
	v_sub_f32_e32 v0, v2, v33
	v_exp_f32_e32 v146, v0
	v_sub_f32_e32 v0, v3, v33
	v_exp_f32_e32 v159, v0
	v_sub_f32_e32 v0, v4, v33
	v_exp_f32_e32 v147, v0
	v_sub_f32_e32 v0, v5, v33
	v_exp_f32_e32 v228, v0
	v_sub_f32_e32 v0, v6, v33
	v_exp_f32_e32 v157, v0
	v_sub_f32_e32 v0, v7, v33
	v_exp_f32_e32 v231, v0
	v_sub_f32_e32 v0, v8, v33
	v_exp_f32_e32 v149, v0
	v_sub_f32_e32 v0, v9, v33
	v_exp_f32_e32 v153, v0
	v_sub_f32_e32 v0, v10, v33
	v_exp_f32_e32 v150, v0
	v_sub_f32_e32 v0, v11, v33
	v_exp_f32_e32 v154, v0
	v_sub_f32_e32 v0, v12, v33
	v_sub_f32_e32 v140, v16, v33
	v_sub_f32_e32 v16, 0xf149f2ca, v32
	v_exp_f32_e32 v151, v0
	v_sub_f32_e32 v0, v13, v33
	v_exp_f32_e32 v16, v16
	v_exp_f32_e32 v155, v0
	v_sub_f32_e32 v0, v14, v33
	v_exp_f32_e32 v152, v0
	v_sub_f32_e32 v0, v15, v33
	v_exp_f32_e32 v156, v0
	v_lshl_add_u32 v215, v169, 2, s4
	v_lshl_add_u32 v179, v171, 2, s4
	s_lshl_b64 s[4:5], s[6:7], 8
	s_waitcnt vmcnt(4)
	s_add_u32 s4, s29, s4
	v_lshlrev_b32_e32 v0, 2, v36
	v_mov_b32_e32 v14, v161
	v_mov_b32_e32 v15, v161
	s_waitcnt vmcnt(7)
	ds_write_b128 v210, v[38:41] offset:16384
	s_waitcnt vmcnt(6)
	ds_write_b128 v211, v[42:45] offset:16384
	s_waitcnt vmcnt(5)
	ds_write_b128 v212, v[46:49] offset:49152
	s_waitcnt vmcnt(4)
	ds_write_b128 v213, v[50:53] offset:49152
	v_sub_f32_e32 v141, v17, v33
	v_sub_f32_e32 v142, v18, v33
	v_sub_f32_e32 v143, v19, v33
	v_sub_f32_e32 v130, v20, v33
	v_sub_f32_e32 v131, v21, v33
	v_sub_f32_e32 v132, v22, v33
	v_sub_f32_e32 v133, v23, v33
	v_sub_f32_e32 v134, v24, v33
	v_sub_f32_e32 v135, v25, v33
	v_sub_f32_e32 v138, v26, v33
	v_sub_f32_e32 v139, v27, v33
	v_sub_f32_e32 v128, v28, v33
	v_sub_f32_e32 v129, v29, v33
	v_sub_f32_e32 v136, v30, v33
	v_sub_f32_e32 v137, v31, v33
	v_cndmask_b32_e64 v224, v16, 1.0, vcc
	s_addc_u32 s5, s28, s5
	v_sub_u32_e32 v223, v188, v0
	v_mov_b32_e32 v0, v161
	v_mov_b32_e32 v1, v161
	v_mov_b32_e32 v2, v161
	v_mov_b32_e32 v3, v161
	v_mov_b32_e32 v4, v161
	v_mov_b32_e32 v5, v161
	v_mov_b32_e32 v6, v161
	v_mov_b32_e32 v7, v161
	v_mov_b32_e32 v8, v161
	v_mov_b32_e32 v9, v161
	v_mov_b32_e32 v10, v161
	v_mov_b32_e32 v11, v161
	v_mov_b32_e32 v12, v161
	v_mov_b32_e32 v13, v161
	v_mov_b64_e32 v[62:63], v[14:15]
	v_mov_b64_e32 v[46:47], v[14:15]
	v_mov_b64_e32 v[30:31], v[14:15]
	s_mov_b32 s33, 2
	v_lshl_add_u64 v[182:183], v[166:167], 0, s[4:5]
	s_sub_i32 s6, 64, s97
	v_mov_b32_e32 v216, 0
	v_mov_b64_e32 v[60:61], v[12:13]
	v_mov_b64_e32 v[58:59], v[10:11]
	v_mov_b64_e32 v[56:57], v[8:9]
	v_mov_b64_e32 v[54:55], v[6:7]
	v_mov_b64_e32 v[52:53], v[4:5]
	v_mov_b64_e32 v[50:51], v[2:3]
	v_mov_b64_e32 v[48:49], v[0:1]
	v_mov_b64_e32 v[44:45], v[12:13]
	v_mov_b64_e32 v[42:43], v[10:11]
	v_mov_b64_e32 v[40:41], v[8:9]
	v_mov_b64_e32 v[38:39], v[6:7]
	v_mov_b64_e32 v[36:37], v[4:5]
	v_mov_b64_e32 v[34:35], v[2:3]
	v_mov_b64_e32 v[32:33], v[0:1]
	v_mov_b64_e32 v[28:29], v[12:13]
	v_mov_b64_e32 v[26:27], v[10:11]
	v_mov_b64_e32 v[24:25], v[8:9]
	v_mov_b64_e32 v[22:23], v[6:7]
	v_mov_b64_e32 v[20:21], v[4:5]
	v_mov_b64_e32 v[18:19], v[2:3]
	v_mov_b64_e32 v[16:17], v[0:1]
	s_waitcnt lgkmcnt(0)
	s_barrier
	v_mov_b32_e32 v250, v148
	v_mov_b32_e32 v251, 1.0
	v_mov_b32_e32 v232, v145
	v_mov_b32_e32 v233, v158
	v_mov_b32_e32 v234, v146
	v_mov_b32_e32 v235, v159
	v_mov_b32_e32 v236, v147
	v_mov_b32_e32 v237, v228
	v_mov_b32_e32 v238, v157
	v_mov_b32_e32 v239, v231
	v_mov_b32_e32 v240, v149
	v_mov_b32_e32 v241, v153
	v_mov_b32_e32 v242, v150
	v_mov_b32_e32 v243, v154
	v_mov_b32_e32 v244, v151
	v_mov_b32_e32 v245, v155
	v_mov_b32_e32 v246, v152
	v_mov_b32_e32 v247, v156
	v_exp_f32_e32 v144, v140
	v_exp_f32_e32 v145, v141
	v_exp_f32_e32 v146, v142
	v_exp_f32_e32 v147, v143
	v_exp_f32_e32 v148, v130
	v_exp_f32_e32 v149, v131
	v_exp_f32_e32 v150, v132
	v_exp_f32_e32 v151, v133
	v_exp_f32_e32 v152, v134
	v_exp_f32_e32 v153, v135
	v_exp_f32_e32 v154, v138
	v_exp_f32_e32 v155, v139
	v_exp_f32_e32 v156, v128
	v_exp_f32_e32 v157, v129
	v_exp_f32_e32 v158, v136
	v_exp_f32_e32 v159, v137
; #define LAS __attribute__((address_space(3)))
; __device__ __forceinline__ float half_add(float v) { auto rr = __builtin_amdgcn_permlane32_swap(__float_as_uint(v), __float_as_uint(v), false, false); return __uint_as_float(rr[0]) + __uint_as_float(rr[1]); }
; __device__ __forceinline__ void finishSM(f32x16& p0, f32x16& p1, float alpha, float& l_reg, bf16x8& pa0, bf16x8& pa1, bf16x8& pa2, bf16x8& pa3) {
; #pragma unroll
;     for (int r = 0; r < 16; ++r) p1[r] = __builtin_amdgcn_exp2f(p1[r]);
;     float ps = 0;
; #pragma unroll
;     for (int r = 0; r < 16; ++r) ps += p0[r];
; #pragma unroll
;     for (int r = 0; r < 16; ++r) ps += p1[r];
;     ps = half_add(ps);
;     l_reg = l_reg * alpha + ps;
;     PK4(p0, 0, pa0); PK4(p0, 8, pa1); PK4(p1, 0, pa2); PK4(p1, 8, pa3);
; }
; __device__ __forceinline__ void qkt(f32x16& p0, f32x16& p1, const LAS unsigned char* Ks, const bf16x8* qr, int r32, int cb0) {
; #pragma unroll
;     for (int i = 0; i < 16; ++i) { p0[i] = 0.f; p1[i] = 0.f; }
; #pragma unroll
;     for (int d0 = 0; d0 < 4; ++d0) { const int cb = cb0 + d0 * 32;
;         const bf16x8 b0 = *(const LAS bf16x8*)(Ks + KSWZ(r32, cb));
;         const bf16x8 b1 = *(const LAS bf16x8*)(Ks + KSWZ(32 + r32, cb));
;         p0 = __builtin_amdgcn_mfma_f32_32x32x16_bf16(b0, qr[d0], p0, 0, 0, 0);
;         p1 = __builtin_amdgcn_mfma_f32_32x32x16_bf16(b1, qr[d0], p1, 0, 0, 0); }
; }
.Lmb_loop:
	s_mov_b32 s28, 0
	v_mov_b32_e32 v249, v181
	s_cmpk_lt_i32 s6, 0xfd93
	s_cbranch_scc1 .Lmb_cls_h1
	v_mov_b32_e32 v249, v217
	s_cmpk_gt_i32 s6, 0x24d
	s_cbranch_scc1 .Lmb_cls_h1
	s_mov_b32 s28, 1
	v_mov_b32_e32 v249, 0
.Lmb_cls_h1:
	ds_read_b128 v[64:67], v219 offset:49152
	ds_read_b128 v[68:71], v219 offset:57344
	ds_read_b128 v[128:131], v220 offset:49152
	ds_read_b128 v[132:135], v220 offset:57344
	ds_read_b128 v[136:139], v221 offset:49152
	ds_read_b128 v[140:143], v221 offset:57344
	v_add_f32_e32 v254, v232, v233
	v_add_f32_e32 v255, v234, v235
	v_add_f32_e32 v254, v254, v236
	v_add_f32_e32 v255, v255, v237
	v_add_f32_e32 v254, v254, v238
	v_add_f32_e32 v255, v255, v239
	v_add_f32_e32 v254, v254, v240
	v_add_f32_e32 v255, v255, v241
	v_add_f32_e32 v254, v254, v242
	v_add_f32_e32 v255, v255, v243
	v_add_f32_e32 v254, v254, v244
	v_add_f32_e32 v255, v255, v245
	v_add_f32_e32 v254, v254, v246
	v_add_f32_e32 v255, v255, v247
	v_add_f32_e32 v254, v254, v144
	v_add_f32_e32 v255, v255, v145
	v_add_f32_e32 v254, v254, v146
	v_add_f32_e32 v255, v255, v147
	v_add_f32_e32 v254, v254, v148
	v_add_f32_e32 v255, v255, v149
	v_add_f32_e32 v254, v254, v150
	v_add_f32_e32 v255, v255, v151
	v_add_f32_e32 v254, v254, v152
	v_add_f32_e32 v255, v255, v153
	v_add_f32_e32 v254, v254, v154
	v_add_f32_e32 v255, v255, v155
	v_add_f32_e32 v254, v254, v156
	v_add_f32_e32 v255, v255, v157
	v_add_f32_e32 v254, v254, v158
	v_add_f32_e32 v255, v255, v159
	v_add_f32_e32 v254, v254, v255
	v_mov_b32_e32 v255, v254
	s_waitcnt lgkmcnt(5)
	v_mfma_f32_32x32x16_bf16 v[80:95], v[64:67], v[108:111], 0
	v_permlane32_swap_b32_e32 v254, v255
	v_cvt_pk_bf16_f32 v232, v232, v233
	v_cvt_pk_bf16_f32 v233, v234, v235
	v_cvt_pk_bf16_f32 v234, v236, v237
	v_add_f32_e32 v254, v254, v255
	v_fma_f32 v216, v216, v251, v254
	s_waitcnt lgkmcnt(4)
	v_mfma_f32_32x32x16_bf16 v[64:79], v[68:71], v[108:111], 0
	v_cvt_pk_bf16_f32 v235, v238, v239
	v_cvt_pk_bf16_f32 v236, v240, v241
	v_cvt_pk_bf16_f32 v237, v242, v243
	v_cvt_pk_bf16_f32 v238, v244, v245
	v_cvt_pk_bf16_f32 v239, v246, v247
	v_cvt_pk_bf16_f32 v144, v144, v145
	s_waitcnt lgkmcnt(3)
	v_mfma_f32_32x32x16_bf16 v[80:95], v[128:131], v[104:107], v[80:95]
	v_cvt_pk_bf16_f32 v145, v146, v147
	v_cvt_pk_bf16_f32 v146, v148, v149
	v_cvt_pk_bf16_f32 v147, v150, v151
	v_cvt_pk_bf16_f32 v148, v152, v153
	v_cvt_pk_bf16_f32 v149, v154, v155
	v_cvt_pk_bf16_f32 v150, v156, v157
	s_waitcnt lgkmcnt(2)
	v_mfma_f32_32x32x16_bf16 v[64:79], v[132:135], v[104:107], v[64:79]
	v_cvt_pk_bf16_f32 v151, v158, v159
	ds_read_b128 v[128:131], v222 offset:49152
	ds_read_b128 v[132:135], v222 offset:57344
	s_cmp_eq_u32 s28, 1
	s_cbranch_scc1 .Lmb_qkn_h1
	ds_read_b64_tr_b16 v[240:241], v175 offset:0
	ds_read_b64_tr_b16 v[242:243], v175 offset:2048
	ds_read_b64_tr_b16 v[244:245], v175 offset:4096
	ds_read_b64_tr_b16 v[246:247], v175 offset:6144
	ds_read_b64_tr_b16 v[152:153], v175 offset:8192
	ds_read_b64_tr_b16 v[154:155], v175 offset:10240
	ds_read_b64_tr_b16 v[156:157], v175 offset:12288
	ds_read_b64_tr_b16 v[158:159], v175 offset:14336
	s_waitcnt lgkmcnt(11)
	v_mfma_f32_32x32x16_bf16 v[80:95], v[136:139], v[100:103], v[80:95]
	v_permlane32_swap_b32_e32 v232, v234
	v_permlane32_swap_b32_e32 v233, v235
	v_permlane32_swap_b32_e32 v236, v238
	v_permlane32_swap_b32_e32 v237, v239
	s_waitcnt lgkmcnt(10)
	v_mfma_f32_32x32x16_bf16 v[64:79], v[140:143], v[100:103], v[64:79]
	v_permlane32_swap_b32_e32 v144, v146
	v_permlane32_swap_b32_e32 v145, v147
	v_permlane32_swap_b32_e32 v148, v150
	v_permlane32_swap_b32_e32 v149, v151
	s_waitcnt lgkmcnt(9)
	v_mfma_f32_32x32x16_bf16 v[80:95], v[128:131], v[96:99], v[80:95]
	s_waitcnt lgkmcnt(8)
	v_mfma_f32_32x32x16_bf16 v[64:79], v[132:135], v[96:99], v[64:79]
	s_branch .Lmb_qkj_h1
.Lmb_qkn_h1:
	s_waitcnt lgkmcnt(3)
	v_mfma_f32_32x32x16_bf16 v[80:95], v[136:139], v[100:103], v[80:95]
	v_permlane32_swap_b32_e32 v232, v234
	v_permlane32_swap_b32_e32 v233, v235
	v_permlane32_swap_b32_e32 v236, v238
	v_permlane32_swap_b32_e32 v237, v239
	s_waitcnt lgkmcnt(2)
	v_mfma_f32_32x32x16_bf16 v[64:79], v[140:143], v[100:103], v[64:79]
	v_permlane32_swap_b32_e32 v144, v146
	v_permlane32_swap_b32_e32 v145, v147
	v_permlane32_swap_b32_e32 v148, v150
	v_permlane32_swap_b32_e32 v149, v151
	s_waitcnt lgkmcnt(1)
	v_mfma_f32_32x32x16_bf16 v[80:95], v[128:131], v[96:99], v[80:95]
	s_waitcnt lgkmcnt(0)
	v_mfma_f32_32x32x16_bf16 v[64:79], v[132:135], v[96:99], v[64:79]
; #define LAS __attribute__((address_space(3)))
; __device__ __forceinline__ void partialSM(f32x16& p0, f32x16& p1, const LAS float* tbp, int relc, float cL, float cR, float& m_reg, float& mn, float& alpha) {
;     float cb = 0.f;
;     if (relc + 63 <= -559) cb = cL;
;     else if (relc - 31 >= 559) cb = cR;
;     else {
; #pragma unroll
;         for (int r = 0; r < 16; ++r) { p0[r] += tbp[(r & 3) + 8 * (r >> 2)]; p1[r] += tbp[32 + (r & 3) + 8 * (r >> 2)]; }
;     }
;     float pmax = p0[0];
; #pragma unroll
;     for (int r = 1; r < 16; ++r) pmax = fmaxf(pmax, p0[r]);
; #pragma unroll
;     for (int r = 0; r < 16; ++r) pmax = fmaxf(pmax, p1[r]);
;     pmax = half_max(pmax) + cb;
;     if (__builtin_expect(__all(pmax - m_reg <= 8.f), 1)) { mn = m_reg; alpha = 1.f; }
;     else { mn = fmaxf(m_reg, pmax); alpha = __builtin_amdgcn_exp2f(m_reg - mn); m_reg = mn; }
;     const float sh = mn - cb;
; #pragma unroll
;     for (int r = 0; r < 16; ++r) { p0[r] -= sh; p1[r] -= sh; }
; #pragma unroll
;     for (int r = 0; r < 16; ++r) p0[r] = __builtin_amdgcn_exp2f(p0[r]);
; }
; template <int D0> __device__ __forceinline__ void pv_one(f32x16& od, int vb, bf16x8 pa0, bf16x8 pa1, bf16x8 pa2, bf16x8 pa3) {
;     s16x4 l0 = tr_read<v_rd_off(D0, 0, 0)>(vb), h0 = tr_read<v_rd_off(D0, 0, 1)>(vb), l1 = tr_read<v_rd_off(D0, 1, 0)>(vb), h1 = tr_read<v_rd_off(D0, 1, 1)>(vb);
;     s16x4 l2 = tr_read<v_rd_off(D0, 2, 0)>(vb), h2 = tr_read<v_rd_off(D0, 2, 1)>(vb), l3 = tr_read<v_rd_off(D0, 3, 0)>(vb), h3 = tr_read<v_rd_off(D0, 3, 1)>(vb);
;     asm volatile("s_waitcnt lgkmcnt(0)" : "+v"(l0), "+v"(h0), "+v"(l1), "+v"(h1), "+v"(l2), "+v"(h2), "+v"(l3), "+v"(h3) :: "memory");
;     od = __builtin_amdgcn_mfma_f32_32x32x16_bf16(pa0, PKV(l0, h0), od, 0, 0, 0);
;     od = __builtin_amdgcn_mfma_f32_32x32x16_bf16(pa1, PKV(l1, h1), od, 0, 0, 0);
;     od = __builtin_amdgcn_mfma_f32_32x32x16_bf16(pa2, PKV(l2, h2), od, 0, 0, 0);
;     od = __builtin_amdgcn_mfma_f32_32x32x16_bf16(pa3, PKV(l3, h3), od, 0, 0, 0);
; }
; __device__ __forceinline__ void pv_d0(f32x16* o, int vb, bf16x8 pa0, bf16x8 pa1, bf16x8 pa2, bf16x8 pa3) {
;     pv_one<0>(o[0], vb, pa0, pa1, pa2, pa3); pv_one<1>(o[1], vb, pa0, pa1, pa2, pa3); pv_one<2>(o[2], vb, pa0, pa1, pa2, pa3); pv_one<3>(o[3], vb, pa0, pa1, pa2, pa3);
; }
.Lmb_qkj_h1:
	s_mov_b32 s4, 0xffee0000
	v_add_co_u32_e32 v132, vcc, s4, v182
	s_mov_b32 s4, 0xfff40000
	s_nop 0
	v_addc_co_u32_e32 v133, vcc, -1, v183, vcc
	v_add_co_u32_e32 v136, vcc, s4, v182
	s_nop 1
	v_addc_co_u32_e32 v137, vcc, -1, v183, vcc
	global_load_dwordx4 v[128:131], v[132:133], off
	s_nop 0
	global_load_dwordx4 v[132:135], v[132:133], off offset:-2048
	s_nop 0
	global_load_dwordx4 v[140:143], v[136:137], off
	s_nop 0
	global_load_dwordx4 v[136:139], v[136:137], off offset:-2048
	s_cmp_eq_u32 s28, 1
	s_cbranch_scc0 .Lmb_pv_h1
	ds_read2_b32 v[240:241], v223 offset1:1
	ds_read2_b32 v[242:243], v223 offset0:2 offset1:3
	ds_read2_b32 v[244:245], v223 offset0:8 offset1:9
	ds_read2_b32 v[246:247], v223 offset0:10 offset1:11
	ds_read2_b32 v[152:153], v223 offset0:16 offset1:17
	ds_read2_b32 v[154:155], v223 offset0:18 offset1:19
	ds_read2_b32 v[156:157], v223 offset0:24 offset1:25
	ds_read2_b32 v[158:159], v223 offset0:26 offset1:27
	s_waitcnt lgkmcnt(0)
	v_pk_add_f32 v[80:81], v[80:81], v[240:241]
	v_pk_add_f32 v[82:83], v[82:83], v[242:243]
	v_pk_add_f32 v[84:85], v[84:85], v[244:245]
	v_pk_add_f32 v[86:87], v[86:87], v[246:247]
	v_pk_add_f32 v[88:89], v[88:89], v[152:153]
	v_pk_add_f32 v[90:91], v[90:91], v[154:155]
	v_pk_add_f32 v[92:93], v[92:93], v[156:157]
	v_pk_add_f32 v[94:95], v[94:95], v[158:159]
	ds_read2_b32 v[240:241], v223 offset0:32 offset1:33
	ds_read2_b32 v[242:243], v223 offset0:34 offset1:35
	ds_read2_b32 v[244:245], v223 offset0:40 offset1:41
	ds_read2_b32 v[246:247], v223 offset0:42 offset1:43
	ds_read2_b32 v[152:153], v223 offset0:48 offset1:49
	ds_read2_b32 v[154:155], v223 offset0:50 offset1:51
	ds_read2_b32 v[156:157], v223 offset0:56 offset1:57
	ds_read2_b32 v[158:159], v223 offset0:58 offset1:59
	s_waitcnt lgkmcnt(0)
	v_pk_add_f32 v[64:65], v[64:65], v[240:241]
	v_pk_add_f32 v[66:67], v[66:67], v[242:243]
	v_pk_add_f32 v[68:69], v[68:69], v[244:245]
	v_pk_add_f32 v[70:71], v[70:71], v[246:247]
	v_pk_add_f32 v[72:73], v[72:73], v[152:153]
	v_pk_add_f32 v[74:75], v[74:75], v[154:155]
	v_pk_add_f32 v[76:77], v[76:77], v[156:157]
	v_pk_add_f32 v[78:79], v[78:79], v[158:159]
	ds_read_b64_tr_b16 v[240:241], v175 offset:0
	ds_read_b64_tr_b16 v[242:243], v175 offset:2048
	ds_read_b64_tr_b16 v[244:245], v175 offset:4096
	ds_read_b64_tr_b16 v[246:247], v175 offset:6144
	ds_read_b64_tr_b16 v[152:153], v175 offset:8192
	ds_read_b64_tr_b16 v[154:155], v175 offset:10240
	ds_read_b64_tr_b16 v[156:157], v175 offset:12288
	ds_read_b64_tr_b16 v[158:159], v175 offset:14336
.Lmb_pv_h1:
	s_waitcnt lgkmcnt(0)
	v_mfma_f32_32x32x16_bf16 v[0:15], v[232:235], v[240:243], v[0:15]
	ds_read_b64_tr_b16 v[240:241], v175 offset:512
	ds_read_b64_tr_b16 v[242:243], v175 offset:2560
	v_max3_f32 v254, v80, v81, v82
	v_max3_f32 v255, v83, v84, v85
	v_max3_f32 v254, v254, v86, v87
	v_max3_f32 v255, v255, v88, v89
	v_max3_f32 v254, v254, v90, v91
	v_max3_f32 v255, v255, v92, v93
	v_mfma_f32_32x32x16_bf16 v[0:15], v[236:239], v[244:247], v[0:15]
	ds_read_b64_tr_b16 v[244:245], v175 offset:4608
	ds_read_b64_tr_b16 v[246:247], v175 offset:6656
	v_max3_f32 v254, v254, v94, v95
	v_max3_f32 v255, v255, v64, v65
	v_max3_f32 v254, v254, v66, v67
	v_max3_f32 v255, v255, v68, v69
	v_max3_f32 v254, v254, v70, v71
	v_max3_f32 v255, v255, v72, v73
	v_mfma_f32_32x32x16_bf16 v[0:15], v[144:147], v[152:155], v[0:15]
	ds_read_b64_tr_b16 v[152:153], v175 offset:8704
	ds_read_b64_tr_b16 v[154:155], v175 offset:10752
	v_max3_f32 v254, v254, v74, v75
	v_max3_f32 v255, v255, v76, v77
	v_max3_f32 v254, v254, v78, v79
	v_max_f32_e32 v254, v254, v255
	v_mov_b32_e32 v255, v254
	v_mfma_f32_32x32x16_bf16 v[0:15], v[148:151], v[156:159], v[0:15]
	ds_read_b64_tr_b16 v[156:157], v175 offset:12800
	ds_read_b64_tr_b16 v[158:159], v175 offset:14848
	v_permlane32_swap_b32_e32 v254, v255
	v_max_f32_e32 v254, v254, v255
	v_add_f32_e32 v254, v249, v254
	v_sub_f32_e32 v255, v254, v250
	v_cmp_ge_f32_e32 vcc, s35, v255
	v_max_f32_e32 v255, v250, v254
	s_waitcnt lgkmcnt(0)
	v_mfma_f32_32x32x16_bf16 v[48:63], v[232:235], v[240:243], v[48:63]
	ds_read_b64_tr_b16 v[240:241], v175 offset:1024
	ds_read_b64_tr_b16 v[242:243], v175 offset:3072
	v_sub_f32_e32 v248, v250, v255
	v_exp_f32_e32 v248, v248
	v_sub_f32_e32 v252, v255, v249
	v_sub_f32_e32 v254, v250, v249
	s_cmp_eq_u64 vcc, exec
	s_cselect_b64 s[4:5], -1, 0
	v_cndmask_b32_e64 v251, v248, 1.0, s[4:5]
	v_mfma_f32_32x32x16_bf16 v[48:63], v[236:239], v[244:247], v[48:63]
	ds_read_b64_tr_b16 v[244:245], v175 offset:5120
	ds_read_b64_tr_b16 v[246:247], v175 offset:7168
	v_cndmask_b32_e64 v250, v255, v250, s[4:5]
	v_cndmask_b32_e64 v252, v252, v254, s[4:5]
	v_sub_f32_e32 v80, v80, v252
	v_sub_f32_e32 v81, v81, v252
	v_sub_f32_e32 v82, v82, v252
	v_sub_f32_e32 v83, v83, v252
	v_mfma_f32_32x32x16_bf16 v[48:63], v[144:147], v[152:155], v[48:63]
	ds_read_b64_tr_b16 v[152:153], v175 offset:9216
	ds_read_b64_tr_b16 v[154:155], v175 offset:11264
	v_sub_f32_e32 v84, v84, v252
	v_sub_f32_e32 v85, v85, v252
	v_sub_f32_e32 v86, v86, v252
	v_sub_f32_e32 v87, v87, v252
	v_sub_f32_e32 v88, v88, v252
	v_sub_f32_e32 v89, v89, v252
	v_mfma_f32_32x32x16_bf16 v[48:63], v[148:151], v[156:159], v[48:63]
	ds_read_b64_tr_b16 v[156:157], v175 offset:13312
	ds_read_b64_tr_b16 v[158:159], v175 offset:15360
	v_sub_f32_e32 v90, v90, v252
	v_sub_f32_e32 v91, v91, v252
	v_sub_f32_e32 v92, v92, v252
	v_sub_f32_e32 v93, v93, v252
	v_sub_f32_e32 v94, v94, v252
	v_sub_f32_e32 v95, v95, v252
	s_waitcnt lgkmcnt(0)
; #define SBAR() __builtin_amdgcn_sched_barrier(0)
; #define SLOAD(i, k0) do { sr_[i].vs0 = *(const bf16x8*)(Vh + (size_t)((k0) + sr) * PW + sc); sr_[i].vs1 = *(const bf16x8*)(Vh + (size_t)((k0) + 32 + sr) * PW + sc); \
;     sr_[i].ks0 = *(const bf16x8*)(Kh + (size_t)((k0) + sr) * PW + sc); sr_[i].ks1 = *(const bf16x8*)(Kh + (size_t)((k0) + 32 + sr) * PW + sc); } while (0)
; #define SWRITE(b, i) do { *(LAS bf16x8*)(V_lds + (b) * SHM_V + vst0) = sr_[i].vs0; *(LAS bf16x8*)(V_lds + (b) * SHM_V + vst1) = sr_[i].vs1; const int kc = sc * 2; \
;     *(LAS bf16x8*)(K_lds + (b) * SHM_K + KSWZ(sr, kc)) = sr_[i].ks0; *(LAS bf16x8*)(K_lds + (b) * SHM_K + KSWZ(32 + sr, kc)) = sr_[i].ks1; } while (0)
; #define SWAIT() asm volatile("s_waitcnt vmcnt(4)" ::: "memory")
; #define RESC(a) do { if (__any((a) < 1.f)) { if (hi == 0) al_l[r32] = (a); LDS_WAIT(); \
;     _Pragma("unroll") for (int r = 0; r < 16; ++r) { const float av = al_l[crow(r, hi)]; _Pragma("unroll") for (int d = 0; d < 4; ++d) o[d][r] *= av; } } } while (0)
; __device__ __forceinline__ void unit(LAS unsigned char* lds, const bf16* __restrict__ PROJ, bf16* __restrict__ MIXED, const float* __restrict__ subln_g, float lam, int R0, int seq, int h, int qb) {
;     ...
;         __syncthreads(); SWAIT(); SWRITE(0, SE);
;         RESC(alB); __syncthreads();
;         SBAR(); qkt(pA0, pA1, K_lds, qr, r32, cb0);
;         finishSM(pB0, pB1, alB, l_reg, pa0, pa1, pa2, pa3); SBAR();
;         if (j + 3 < NT) SLOAD(SE, (j + 3) * 64); SBAR();
;         pv_d0(o, vb0 + SHM_V, pa0, pa1, pa2, pa3); partialSM(pA0, pA1, tbq + (j + 1) * 64, rc0 + (j + 1) * 64, cL, cR, m_reg, mnA, alA);
	v_mfma_f32_32x32x16_bf16 v[32:47], v[232:235], v[240:243], v[32:47]
	ds_read_b64_tr_b16 v[240:241], v175 offset:1536
	ds_read_b64_tr_b16 v[242:243], v175 offset:3584
	v_exp_f32_e32 v80, v80
	v_sub_f32_e32 v64, v64, v252
	v_exp_f32_e32 v81, v81
	v_sub_f32_e32 v65, v65, v252
	v_mfma_f32_32x32x16_bf16 v[32:47], v[236:239], v[244:247], v[32:47]
	ds_read_b64_tr_b16 v[244:245], v175 offset:5632
	ds_read_b64_tr_b16 v[246:247], v175 offset:7680
	v_exp_f32_e32 v82, v82
	v_sub_f32_e32 v66, v66, v252
	v_exp_f32_e32 v83, v83
	v_sub_f32_e32 v67, v67, v252
	v_mfma_f32_32x32x16_bf16 v[32:47], v[144:147], v[152:155], v[32:47]
	ds_read_b64_tr_b16 v[152:153], v175 offset:9728
	ds_read_b64_tr_b16 v[154:155], v175 offset:11776
	v_exp_f32_e32 v84, v84
	v_sub_f32_e32 v68, v68, v252
	v_exp_f32_e32 v85, v85
	v_sub_f32_e32 v69, v69, v252
	v_mfma_f32_32x32x16_bf16 v[32:47], v[148:151], v[156:159], v[32:47]
	ds_read_b64_tr_b16 v[156:157], v175 offset:13824
	ds_read_b64_tr_b16 v[158:159], v175 offset:15872
	v_exp_f32_e32 v86, v86
	v_sub_f32_e32 v70, v70, v252
	v_exp_f32_e32 v87, v87
	v_sub_f32_e32 v71, v71, v252
	s_waitcnt lgkmcnt(0)
	v_mfma_f32_32x32x16_bf16 v[16:31], v[232:235], v[240:243], v[16:31]
	v_exp_f32_e32 v88, v88
	v_sub_f32_e32 v72, v72, v252
	v_exp_f32_e32 v89, v89
	v_sub_f32_e32 v73, v73, v252
	v_mfma_f32_32x32x16_bf16 v[16:31], v[236:239], v[244:247], v[16:31]
	v_exp_f32_e32 v90, v90
	v_sub_f32_e32 v74, v74, v252
	v_exp_f32_e32 v91, v91
	v_sub_f32_e32 v75, v75, v252
	v_mfma_f32_32x32x16_bf16 v[16:31], v[144:147], v[152:155], v[16:31]
	v_exp_f32_e32 v92, v92
	v_sub_f32_e32 v76, v76, v252
	v_exp_f32_e32 v93, v93
	v_sub_f32_e32 v77, v77, v252
	v_mfma_f32_32x32x16_bf16 v[16:31], v[148:151], v[156:159], v[16:31]
	v_exp_f32_e32 v94, v94
	v_sub_f32_e32 v78, v78, v252
	v_exp_f32_e32 v95, v95
	v_sub_f32_e32 v79, v79, v252
	s_barrier
	s_waitcnt vmcnt(4)
	ds_write_b128 v210, v[120:123]
	ds_write_b128 v211, v[124:127]
	ds_write_b128 v212, v[112:115] offset:32768
	ds_write_b128 v213, v[116:119] offset:32768
	s_and_b64 vcc, exec, s[4:5]
	s_cbranch_vccnz .Lmb_nr_h1
	s_and_saveexec_b64 s[28:29], s[0:1]
	ds_write_b32 v215, v251 offset:128
	s_or_b64 exec, exec, s[28:29]
	s_waitcnt lgkmcnt(0)
	ds_read_b128 v[112:115], v179 offset:224
	ds_read_b128 v[116:119], v179 offset:192
	ds_read_b128 v[120:123], v179 offset:160
	ds_read_b128 v[124:127], v179 offset:128
	s_waitcnt lgkmcnt(0)
	s_nop 3
	v_pk_mul_f32 v[14:15], v[14:15], v[114:115]
	v_pk_mul_f32 v[12:13], v[12:13], v[112:113]
	v_pk_mul_f32 v[10:11], v[10:11], v[118:119]
	v_pk_mul_f32 v[8:9], v[8:9], v[116:117]
	v_pk_mul_f32 v[6:7], v[6:7], v[122:123]
	v_pk_mul_f32 v[4:5], v[4:5], v[120:121]
	v_pk_mul_f32 v[2:3], v[2:3], v[126:127]
	v_pk_mul_f32 v[0:1], v[0:1], v[124:125]
	v_pk_mul_f32 v[62:63], v[62:63], v[114:115]
	v_pk_mul_f32 v[60:61], v[60:61], v[112:113]
	v_pk_mul_f32 v[58:59], v[58:59], v[118:119]
	v_pk_mul_f32 v[56:57], v[56:57], v[116:117]
	v_pk_mul_f32 v[54:55], v[54:55], v[122:123]
	v_pk_mul_f32 v[52:53], v[52:53], v[120:121]
	v_pk_mul_f32 v[50:51], v[50:51], v[126:127]
	v_pk_mul_f32 v[48:49], v[48:49], v[124:125]
	v_pk_mul_f32 v[46:47], v[46:47], v[114:115]
	v_pk_mul_f32 v[44:45], v[44:45], v[112:113]
	v_pk_mul_f32 v[42:43], v[42:43], v[118:119]
	v_pk_mul_f32 v[40:41], v[40:41], v[116:117]
	v_pk_mul_f32 v[38:39], v[38:39], v[122:123]
	v_pk_mul_f32 v[36:37], v[36:37], v[120:121]
	v_pk_mul_f32 v[34:35], v[34:35], v[126:127]
	v_pk_mul_f32 v[32:33], v[32:33], v[124:125]
	v_pk_mul_f32 v[30:31], v[30:31], v[114:115]
	v_pk_mul_f32 v[28:29], v[28:29], v[112:113]
	v_pk_mul_f32 v[26:27], v[26:27], v[118:119]
	v_pk_mul_f32 v[24:25], v[24:25], v[116:117]
	v_pk_mul_f32 v[22:23], v[22:23], v[122:123]
	v_pk_mul_f32 v[20:21], v[20:21], v[120:121]
	v_pk_mul_f32 v[18:19], v[18:19], v[126:127]
	v_pk_mul_f32 v[16:17], v[16:17], v[124:125]
.Lmb_nr_h1:
	v_exp_f32_e32 v64, v64
	v_exp_f32_e32 v65, v65
	v_exp_f32_e32 v66, v66
	v_exp_f32_e32 v67, v67
	v_exp_f32_e32 v68, v68
	v_exp_f32_e32 v69, v69
	v_exp_f32_e32 v70, v70
	v_exp_f32_e32 v71, v71
	v_exp_f32_e32 v72, v72
	v_exp_f32_e32 v73, v73
	v_exp_f32_e32 v74, v74
	v_exp_f32_e32 v75, v75
	v_exp_f32_e32 v76, v76
	v_exp_f32_e32 v77, v77
	v_exp_f32_e32 v78, v78
	v_exp_f32_e32 v79, v79
	s_waitcnt lgkmcnt(0)
	s_barrier
	s_add_i32 s4, s6, 64
	s_mov_b32 s28, 0
	v_mov_b32_e32 v249, v181
	s_cmpk_lt_i32 s4, 0xfd93
	s_cbranch_scc1 .Lmb_cls_h2
	v_mov_b32_e32 v249, v217
	s_cmpk_gt_i32 s4, 0x24d
	s_cbranch_scc1 .Lmb_cls_h2
	s_mov_b32 s28, 1
	v_mov_b32_e32 v249, 0
; #define LAS __attribute__((address_space(3)))
; #define SBAR() __builtin_amdgcn_sched_barrier(0)
; __device__ __forceinline__ float half_add(float v) { auto rr = __builtin_amdgcn_permlane32_swap(__float_as_uint(v), __float_as_uint(v), false, false); return __uint_as_float(rr[0]) + __uint_as_float(rr[1]); }
; #define SLOAD(i, k0) do { sr_[i].vs0 = *(const bf16x8*)(Vh + (size_t)((k0) + sr) * PW + sc); sr_[i].vs1 = *(const bf16x8*)(Vh + (size_t)((k0) + 32 + sr) * PW + sc); \
;     sr_[i].ks0 = *(const bf16x8*)(Kh + (size_t)((k0) + sr) * PW + sc); sr_[i].ks1 = *(const bf16x8*)(Kh + (size_t)((k0) + 32 + sr) * PW + sc); } while (0)
; __device__ __forceinline__ void finishSM(f32x16& p0, f32x16& p1, float alpha, float& l_reg, bf16x8& pa0, bf16x8& pa1, bf16x8& pa2, bf16x8& pa3) {
; #pragma unroll
;     for (int r = 0; r < 16; ++r) p1[r] = __builtin_amdgcn_exp2f(p1[r]);
;     float ps = 0;
; #pragma unroll
;     for (int r = 0; r < 16; ++r) ps += p0[r];
; #pragma unroll
;     for (int r = 0; r < 16; ++r) ps += p1[r];
;     ps = half_add(ps);
;     l_reg = l_reg * alpha + ps;
;     PK4(p0, 0, pa0); PK4(p0, 8, pa1); PK4(p1, 0, pa2); PK4(p1, 8, pa3);
; }
; __device__ __forceinline__ void qkt(f32x16& p0, f32x16& p1, const LAS unsigned char* Ks, const bf16x8* qr, int r32, int cb0) {
; #pragma unroll
;     for (int i = 0; i < 16; ++i) { p0[i] = 0.f; p1[i] = 0.f; }
; #pragma unroll
;     for (int d0 = 0; d0 < 4; ++d0) { const int cb = cb0 + d0 * 32;
;         const bf16x8 b0 = *(const LAS bf16x8*)(Ks + KSWZ(r32, cb));
;         const bf16x8 b1 = *(const LAS bf16x8*)(Ks + KSWZ(32 + r32, cb));
;         p0 = __builtin_amdgcn_mfma_f32_32x32x16_bf16(b0, qr[d0], p0, 0, 0, 0);
;         p1 = __builtin_amdgcn_mfma_f32_32x32x16_bf16(b1, qr[d0], p1, 0, 0, 0); }
; }
; __device__ __forceinline__ void unit(LAS unsigned char* lds, const bf16* __restrict__ PROJ, bf16* __restrict__ MIXED, const float* __restrict__ subln_g, float lam, int R0, int seq, int h, int qb) {
;     ...
;         SBAR(); qkt(pA0, pA1, K_lds, qr, r32, cb0);
;         finishSM(pB0, pB1, alB, l_reg, pa0, pa1, pa2, pa3); SBAR();
;         if (j + 3 < NT) SLOAD(SE, (j + 3) * 64); SBAR();
.Lmb_cls_h2:
	ds_read_b128 v[144:147], v219 offset:32768
	ds_read_b128 v[148:151], v219 offset:40960
	ds_read_b128 v[112:115], v220 offset:32768
	ds_read_b128 v[116:119], v220 offset:40960
	ds_read_b128 v[120:123], v221 offset:32768
	ds_read_b128 v[124:127], v221 offset:40960
	v_add_f32_e32 v254, v80, v81
	v_add_f32_e32 v255, v82, v83
	v_add_f32_e32 v254, v254, v84
	v_add_f32_e32 v255, v255, v85
	v_add_f32_e32 v254, v254, v86
	v_add_f32_e32 v255, v255, v87
	v_add_f32_e32 v254, v254, v88
	v_add_f32_e32 v255, v255, v89
	v_add_f32_e32 v254, v254, v90
	v_add_f32_e32 v255, v255, v91
	v_add_f32_e32 v254, v254, v92
	v_add_f32_e32 v255, v255, v93
	v_add_f32_e32 v254, v254, v94
	v_add_f32_e32 v255, v255, v95
	v_add_f32_e32 v254, v254, v64
	v_add_f32_e32 v255, v255, v65
	v_add_f32_e32 v254, v254, v66
	v_add_f32_e32 v255, v255, v67
	v_add_f32_e32 v254, v254, v68
	v_add_f32_e32 v255, v255, v69
	v_add_f32_e32 v254, v254, v70
	v_add_f32_e32 v255, v255, v71
	v_add_f32_e32 v254, v254, v72
	v_add_f32_e32 v255, v255, v73
	v_add_f32_e32 v254, v254, v74
	v_add_f32_e32 v255, v255, v75
	v_add_f32_e32 v254, v254, v76
	v_add_f32_e32 v255, v255, v77
	v_add_f32_e32 v254, v254, v78
	v_add_f32_e32 v255, v255, v79
	v_add_f32_e32 v254, v254, v255
	v_mov_b32_e32 v255, v254
	s_waitcnt lgkmcnt(5)
	v_mfma_f32_32x32x16_bf16 v[232:247], v[144:147], v[108:111], 0
	v_permlane32_swap_b32_e32 v254, v255
	v_cvt_pk_bf16_f32 v80, v80, v81
	v_cvt_pk_bf16_f32 v81, v82, v83
	v_cvt_pk_bf16_f32 v82, v84, v85
	v_add_f32_e32 v254, v254, v255
	v_fma_f32 v216, v216, v251, v254
	s_waitcnt lgkmcnt(4)
	v_mfma_f32_32x32x16_bf16 v[144:159], v[148:151], v[108:111], 0
	v_cvt_pk_bf16_f32 v83, v86, v87
	v_cvt_pk_bf16_f32 v84, v88, v89
	v_cvt_pk_bf16_f32 v85, v90, v91
	v_cvt_pk_bf16_f32 v86, v92, v93
	v_cvt_pk_bf16_f32 v87, v94, v95
	v_cvt_pk_bf16_f32 v64, v64, v65
	s_waitcnt lgkmcnt(3)
	v_mfma_f32_32x32x16_bf16 v[232:247], v[112:115], v[104:107], v[232:247]
	v_cvt_pk_bf16_f32 v65, v66, v67
	v_cvt_pk_bf16_f32 v66, v68, v69
	v_cvt_pk_bf16_f32 v67, v70, v71
	v_cvt_pk_bf16_f32 v68, v72, v73
	v_cvt_pk_bf16_f32 v69, v74, v75
	v_cvt_pk_bf16_f32 v70, v76, v77
	s_waitcnt lgkmcnt(2)
	v_mfma_f32_32x32x16_bf16 v[144:159], v[116:119], v[104:107], v[144:159]
	v_cvt_pk_bf16_f32 v71, v78, v79
	ds_read_b128 v[112:115], v222 offset:32768
	ds_read_b128 v[116:119], v222 offset:40960
	s_cmp_eq_u32 s28, 1
	s_cbranch_scc1 .Lmb_qkn_h2
	ds_read_b64_tr_b16 v[88:89], v186 offset:0
	ds_read_b64_tr_b16 v[90:91], v186 offset:2048
	ds_read_b64_tr_b16 v[92:93], v186 offset:4096
	ds_read_b64_tr_b16 v[94:95], v186 offset:6144
	ds_read_b64_tr_b16 v[72:73], v186 offset:8192
	ds_read_b64_tr_b16 v[74:75], v186 offset:10240
	ds_read_b64_tr_b16 v[76:77], v186 offset:12288
	ds_read_b64_tr_b16 v[78:79], v186 offset:14336
	s_waitcnt lgkmcnt(11)
	v_mfma_f32_32x32x16_bf16 v[232:247], v[120:123], v[100:103], v[232:247]
	v_permlane32_swap_b32_e32 v80, v82
	v_permlane32_swap_b32_e32 v81, v83
	v_permlane32_swap_b32_e32 v84, v86
	v_permlane32_swap_b32_e32 v85, v87
	s_waitcnt lgkmcnt(10)
	v_mfma_f32_32x32x16_bf16 v[144:159], v[124:127], v[100:103], v[144:159]
	v_permlane32_swap_b32_e32 v64, v66
	v_permlane32_swap_b32_e32 v65, v67
	v_permlane32_swap_b32_e32 v68, v70
	v_permlane32_swap_b32_e32 v69, v71
	s_waitcnt lgkmcnt(9)
	v_mfma_f32_32x32x16_bf16 v[232:247], v[112:115], v[96:99], v[232:247]
	s_waitcnt lgkmcnt(8)
	v_mfma_f32_32x32x16_bf16 v[144:159], v[116:119], v[96:99], v[144:159]
	s_branch .Lmb_qkj_h2
.Lmb_qkn_h2:
	s_waitcnt lgkmcnt(3)
	v_mfma_f32_32x32x16_bf16 v[232:247], v[120:123], v[100:103], v[232:247]
	v_permlane32_swap_b32_e32 v80, v82
	v_permlane32_swap_b32_e32 v81, v83
	v_permlane32_swap_b32_e32 v84, v86
	v_permlane32_swap_b32_e32 v85, v87
	s_waitcnt lgkmcnt(2)
	v_mfma_f32_32x32x16_bf16 v[144:159], v[124:127], v[100:103], v[144:159]
	v_permlane32_swap_b32_e32 v64, v66
	v_permlane32_swap_b32_e32 v65, v67
	v_permlane32_swap_b32_e32 v68, v70
	v_permlane32_swap_b32_e32 v69, v71
	s_waitcnt lgkmcnt(1)
	v_mfma_f32_32x32x16_bf16 v[232:247], v[112:115], v[96:99], v[232:247]
	s_waitcnt lgkmcnt(0)
	v_mfma_f32_32x32x16_bf16 v[144:159], v[116:119], v[96:99], v[144:159]
.Lmb_qkj_h2:
	s_add_i32 s33, s33, 2
	s_cmp_ge_u32 s33, s90
	s_cselect_b64 s[26:27], -1, 0
	s_and_b64 vcc, exec, s[26:27]
	s_cbranch_vccnz .Lmb_skipld
	v_add_co_u32_e32 v112, vcc, 0xfffa0000, v182
	s_nop 1
	v_addc_co_u32_e32 v113, vcc, -1, v183, vcc
	global_load_dwordx4 v[120:123], v[112:113], off
	s_nop 0
	global_load_dwordx4 v[112:115], v[112:113], off offset:-2048
	s_nop 0
	global_load_dwordx4 v[124:127], v[182:183], off
	global_load_dwordx4 v[116:119], v[182:183], off offset:-2048
; #define LAS __attribute__((address_space(3)))
; #define SBAR() __builtin_amdgcn_sched_barrier(0)
; __device__ __forceinline__ float half_max(float v) { auto rr = __builtin_amdgcn_permlane32_swap(__float_as_uint(v), __float_as_uint(v), false, false); return fmaxf(__uint_as_float(rr[0]), __uint_as_float(rr[1])); }
; #define SLOAD(i, k0) do { sr_[i].vs0 = *(const bf16x8*)(Vh + (size_t)((k0) + sr) * PW + sc); sr_[i].vs1 = *(const bf16x8*)(Vh + (size_t)((k0) + 32 + sr) * PW + sc); \
;     sr_[i].ks0 = *(const bf16x8*)(Kh + (size_t)((k0) + sr) * PW + sc); sr_[i].ks1 = *(const bf16x8*)(Kh + (size_t)((k0) + 32 + sr) * PW + sc); } while (0)
; #define SWAIT() asm volatile("s_waitcnt vmcnt(4)" ::: "memory")
; __device__ __forceinline__ void partialSM(f32x16& p0, f32x16& p1, const LAS float* tbp, int relc, float cL, float cR, float& m_reg, float& mn, float& alpha) {
;     float cb = 0.f;
;     if (relc + 63 <= -559) cb = cL;
;     else if (relc - 31 >= 559) cb = cR;
;     else {
; #pragma unroll
;         for (int r = 0; r < 16; ++r) { p0[r] += tbp[(r & 3) + 8 * (r >> 2)]; p1[r] += tbp[32 + (r & 3) + 8 * (r >> 2)]; }
;     }
;     float pmax = p0[0];
; #pragma unroll
;     for (int r = 1; r < 16; ++r) pmax = fmaxf(pmax, p0[r]);
; #pragma unroll
;     for (int r = 0; r < 16; ++r) pmax = fmaxf(pmax, p1[r]);
;     pmax = half_max(pmax) + cb;
;     if (__builtin_expect(__all(pmax - m_reg <= 8.f), 1)) { mn = m_reg; alpha = 1.f; }
;     else { mn = fmaxf(m_reg, pmax); alpha = __builtin_amdgcn_exp2f(m_reg - mn); m_reg = mn; }
;     const float sh = mn - cb;
; #pragma unroll
;     for (int r = 0; r < 16; ++r) { p0[r] -= sh; p1[r] -= sh; }
; #pragma unroll
;     for (int r = 0; r < 16; ++r) p0[r] = __builtin_amdgcn_exp2f(p0[r]);
; }
; __device__ __forceinline__ void unit(LAS unsigned char* lds, const bf16* __restrict__ PROJ, bf16* __restrict__ MIXED, const float* __restrict__ subln_g, float lam, int R0, int seq, int h, int qb) {
;     ...
;         if (j + 3 < NT) SLOAD(SE, (j + 3) * 64); SBAR();
;         pv_d0(o, vb0 + SHM_V, pa0, pa1, pa2, pa3); partialSM(pA0, pA1, tbq + (j + 1) * 64, rc0 + (j + 1) * 64, cL, cR, m_reg, mnA, alA);
;         __syncthreads(); SWAIT(); SWRITE(1, SO);
.Lmb_skipld:
	s_cmp_eq_u32 s28, 1
	s_cbranch_scc0 .Lmb_pv_h2
	ds_read2_b32 v[88:89], v223 offset0:64 offset1:65
	ds_read2_b32 v[90:91], v223 offset0:66 offset1:67
	ds_read2_b32 v[92:93], v223 offset0:72 offset1:73
	ds_read2_b32 v[94:95], v223 offset0:74 offset1:75
	ds_read2_b32 v[72:73], v223 offset0:80 offset1:81
	ds_read2_b32 v[74:75], v223 offset0:82 offset1:83
	ds_read2_b32 v[76:77], v223 offset0:88 offset1:89
	ds_read2_b32 v[78:79], v223 offset0:90 offset1:91
	s_waitcnt lgkmcnt(0)
	v_pk_add_f32 v[232:233], v[232:233], v[88:89]
	v_pk_add_f32 v[234:235], v[234:235], v[90:91]
	v_pk_add_f32 v[236:237], v[236:237], v[92:93]
	v_pk_add_f32 v[238:239], v[238:239], v[94:95]
	v_pk_add_f32 v[240:241], v[240:241], v[72:73]
	v_pk_add_f32 v[242:243], v[242:243], v[74:75]
	v_pk_add_f32 v[244:245], v[244:245], v[76:77]
	v_pk_add_f32 v[246:247], v[246:247], v[78:79]
	ds_read2_b32 v[88:89], v223 offset0:96 offset1:97
	ds_read2_b32 v[90:91], v223 offset0:98 offset1:99
	ds_read2_b32 v[92:93], v223 offset0:104 offset1:105
	ds_read2_b32 v[94:95], v223 offset0:106 offset1:107
	ds_read2_b32 v[72:73], v223 offset0:112 offset1:113
	ds_read2_b32 v[74:75], v223 offset0:114 offset1:115
	ds_read2_b32 v[76:77], v223 offset0:120 offset1:121
	ds_read2_b32 v[78:79], v223 offset0:122 offset1:123
	s_waitcnt lgkmcnt(0)
	v_pk_add_f32 v[144:145], v[144:145], v[88:89]
	v_pk_add_f32 v[146:147], v[146:147], v[90:91]
	v_pk_add_f32 v[148:149], v[148:149], v[92:93]
	v_pk_add_f32 v[150:151], v[150:151], v[94:95]
	v_pk_add_f32 v[152:153], v[152:153], v[72:73]
	v_pk_add_f32 v[154:155], v[154:155], v[74:75]
	v_pk_add_f32 v[156:157], v[156:157], v[76:77]
	v_pk_add_f32 v[158:159], v[158:159], v[78:79]
	ds_read_b64_tr_b16 v[88:89], v186 offset:0
	ds_read_b64_tr_b16 v[90:91], v186 offset:2048
	ds_read_b64_tr_b16 v[92:93], v186 offset:4096
	ds_read_b64_tr_b16 v[94:95], v186 offset:6144
	ds_read_b64_tr_b16 v[72:73], v186 offset:8192
	ds_read_b64_tr_b16 v[74:75], v186 offset:10240
	ds_read_b64_tr_b16 v[76:77], v186 offset:12288
	ds_read_b64_tr_b16 v[78:79], v186 offset:14336
.Lmb_pv_h2:
	s_waitcnt lgkmcnt(0)
	v_mfma_f32_32x32x16_bf16 v[0:15], v[80:83], v[88:91], v[0:15]
	ds_read_b64_tr_b16 v[88:89], v186 offset:512
	ds_read_b64_tr_b16 v[90:91], v186 offset:2560
	v_max3_f32 v254, v232, v233, v234
	v_max3_f32 v255, v235, v236, v237
	v_max3_f32 v254, v254, v238, v239
	v_max3_f32 v255, v255, v240, v241
	v_max3_f32 v254, v254, v242, v243
	v_max3_f32 v255, v255, v244, v245
	v_mfma_f32_32x32x16_bf16 v[0:15], v[84:87], v[92:95], v[0:15]
	ds_read_b64_tr_b16 v[92:93], v186 offset:4608
	ds_read_b64_tr_b16 v[94:95], v186 offset:6656
	v_max3_f32 v254, v254, v246, v247
	v_max3_f32 v255, v255, v144, v145
	v_max3_f32 v254, v254, v146, v147
	v_max3_f32 v255, v255, v148, v149
	v_max3_f32 v254, v254, v150, v151
	v_max3_f32 v255, v255, v152, v153
	v_mfma_f32_32x32x16_bf16 v[0:15], v[64:67], v[72:75], v[0:15]
	ds_read_b64_tr_b16 v[72:73], v186 offset:8704
	ds_read_b64_tr_b16 v[74:75], v186 offset:10752
	v_max3_f32 v254, v254, v154, v155
	v_max3_f32 v255, v255, v156, v157
	v_max3_f32 v254, v254, v158, v159
	v_max_f32_e32 v254, v254, v255
	v_mov_b32_e32 v255, v254
	v_mfma_f32_32x32x16_bf16 v[0:15], v[68:71], v[76:79], v[0:15]
	ds_read_b64_tr_b16 v[76:77], v186 offset:12800
	ds_read_b64_tr_b16 v[78:79], v186 offset:14848
	v_permlane32_swap_b32_e32 v254, v255
	v_max_f32_e32 v254, v254, v255
	v_add_f32_e32 v254, v249, v254
	v_sub_f32_e32 v255, v254, v250
	v_cmp_ge_f32_e32 vcc, s35, v255
	v_max_f32_e32 v255, v250, v254
	s_waitcnt lgkmcnt(0)
	v_mfma_f32_32x32x16_bf16 v[48:63], v[80:83], v[88:91], v[48:63]
	ds_read_b64_tr_b16 v[88:89], v186 offset:1024
	ds_read_b64_tr_b16 v[90:91], v186 offset:3072
	v_sub_f32_e32 v248, v250, v255
	v_exp_f32_e32 v248, v248
	v_sub_f32_e32 v252, v255, v249
	v_sub_f32_e32 v254, v250, v249
	s_cmp_eq_u64 vcc, exec
	s_cselect_b64 s[4:5], -1, 0
	v_cndmask_b32_e64 v251, v248, 1.0, s[4:5]
	v_mfma_f32_32x32x16_bf16 v[48:63], v[84:87], v[92:95], v[48:63]
	ds_read_b64_tr_b16 v[92:93], v186 offset:5120
	ds_read_b64_tr_b16 v[94:95], v186 offset:7168
	v_cndmask_b32_e64 v250, v255, v250, s[4:5]
	v_cndmask_b32_e64 v252, v252, v254, s[4:5]
	v_sub_f32_e32 v232, v232, v252
	v_sub_f32_e32 v233, v233, v252
	v_sub_f32_e32 v234, v234, v252
	v_sub_f32_e32 v235, v235, v252
	v_mfma_f32_32x32x16_bf16 v[48:63], v[64:67], v[72:75], v[48:63]
	ds_read_b64_tr_b16 v[72:73], v186 offset:9216
	ds_read_b64_tr_b16 v[74:75], v186 offset:11264
	v_sub_f32_e32 v236, v236, v252
	v_sub_f32_e32 v237, v237, v252
	v_sub_f32_e32 v238, v238, v252
	v_sub_f32_e32 v239, v239, v252
	v_sub_f32_e32 v240, v240, v252
	v_sub_f32_e32 v241, v241, v252
	v_mfma_f32_32x32x16_bf16 v[48:63], v[68:71], v[76:79], v[48:63]
	ds_read_b64_tr_b16 v[76:77], v186 offset:13312
	ds_read_b64_tr_b16 v[78:79], v186 offset:15360
	v_sub_f32_e32 v242, v242, v252
	v_sub_f32_e32 v243, v243, v252
	v_sub_f32_e32 v244, v244, v252
	v_sub_f32_e32 v245, v245, v252
	v_sub_f32_e32 v246, v246, v252
	v_sub_f32_e32 v247, v247, v252
	s_waitcnt lgkmcnt(0)
	v_mfma_f32_32x32x16_bf16 v[32:47], v[80:83], v[88:91], v[32:47]
	ds_read_b64_tr_b16 v[88:89], v186 offset:1536
	ds_read_b64_tr_b16 v[90:91], v186 offset:3584
	v_exp_f32_e32 v232, v232
	v_sub_f32_e32 v144, v144, v252
	v_exp_f32_e32 v233, v233
	v_sub_f32_e32 v145, v145, v252
	v_mfma_f32_32x32x16_bf16 v[32:47], v[84:87], v[92:95], v[32:47]
	ds_read_b64_tr_b16 v[92:93], v186 offset:5632
	ds_read_b64_tr_b16 v[94:95], v186 offset:7680
	v_exp_f32_e32 v234, v234
	v_sub_f32_e32 v146, v146, v252
	v_exp_f32_e32 v235, v235
	v_sub_f32_e32 v147, v147, v252
	v_mfma_f32_32x32x16_bf16 v[32:47], v[64:67], v[72:75], v[32:47]
	ds_read_b64_tr_b16 v[72:73], v186 offset:9728
	ds_read_b64_tr_b16 v[74:75], v186 offset:11776
	v_exp_f32_e32 v236, v236
	v_sub_f32_e32 v148, v148, v252
	v_exp_f32_e32 v237, v237
	v_sub_f32_e32 v149, v149, v252
	v_mfma_f32_32x32x16_bf16 v[32:47], v[68:71], v[76:79], v[32:47]
	ds_read_b64_tr_b16 v[76:77], v186 offset:13824
	ds_read_b64_tr_b16 v[78:79], v186 offset:15872
	v_exp_f32_e32 v238, v238
	v_sub_f32_e32 v150, v150, v252
	v_exp_f32_e32 v239, v239
	v_sub_f32_e32 v151, v151, v252
	s_waitcnt lgkmcnt(0)
	v_mfma_f32_32x32x16_bf16 v[16:31], v[80:83], v[88:91], v[16:31]
	v_exp_f32_e32 v240, v240
	v_sub_f32_e32 v152, v152, v252
	v_exp_f32_e32 v241, v241
	v_sub_f32_e32 v153, v153, v252
	v_mfma_f32_32x32x16_bf16 v[16:31], v[84:87], v[92:95], v[16:31]
	v_exp_f32_e32 v242, v242
	v_sub_f32_e32 v154, v154, v252
	v_exp_f32_e32 v243, v243
	v_sub_f32_e32 v155, v155, v252
	v_mfma_f32_32x32x16_bf16 v[16:31], v[64:67], v[72:75], v[16:31]
	v_exp_f32_e32 v244, v244
	v_sub_f32_e32 v156, v156, v252
	v_exp_f32_e32 v245, v245
	v_sub_f32_e32 v157, v157, v252
	v_mfma_f32_32x32x16_bf16 v[16:31], v[68:71], v[76:79], v[16:31]
	v_exp_f32_e32 v246, v246
	v_sub_f32_e32 v158, v158, v252
	v_exp_f32_e32 v247, v247
	v_sub_f32_e32 v159, v159, v252
	s_barrier
	s_waitcnt vmcnt(4)
	s_and_b64 vcc, exec, s[26:27]
	s_cbranch_vccz .Lmb_w2
	s_waitcnt vmcnt(0)
; #define SWRITE(b, i) do { *(LAS bf16x8*)(V_lds + (b) * SHM_V + vst0) = sr_[i].vs0; *(LAS bf16x8*)(V_lds + (b) * SHM_V + vst1) = sr_[i].vs1; const int kc = sc * 2; \
;     *(LAS bf16x8*)(K_lds + (b) * SHM_K + KSWZ(sr, kc)) = sr_[i].ks0; *(LAS bf16x8*)(K_lds + (b) * SHM_K + KSWZ(32 + sr, kc)) = sr_[i].ks1; } while (0)
; #define SWAIT() asm volatile("s_waitcnt vmcnt(4)" ::: "memory")
; #define RESC(a) do { if (__any((a) < 1.f)) { if (hi == 0) al_l[r32] = (a); LDS_WAIT(); \
;     _Pragma("unroll") for (int r = 0; r < 16; ++r) { const float av = al_l[crow(r, hi)]; _Pragma("unroll") for (int d = 0; d < 4; ++d) o[d][r] *= av; } } } while (0)
; __device__ __forceinline__ void unit(LAS unsigned char* lds, const bf16* __restrict__ PROJ, bf16* __restrict__ MIXED, const float* __restrict__ subln_g, float lam, int R0, int seq, int h, int qb) {
;     ...
;         __syncthreads(); SWAIT(); SWRITE(1, SO);
;         RESC(alA); __syncthreads();
;     }
.Lmb_w2:
	ds_write_b128 v210, v[128:131] offset:16384
	ds_write_b128 v211, v[140:143] offset:16384
	ds_write_b128 v212, v[132:135] offset:49152
	ds_write_b128 v213, v[136:139] offset:49152
	s_and_b64 vcc, exec, s[4:5]
	s_cbranch_vccnz .Lmb_nr_h2
	s_and_saveexec_b64 s[28:29], s[0:1]
	ds_write_b32 v215, v251 offset:128
	s_or_b64 exec, exec, s[28:29]
	s_waitcnt lgkmcnt(0)
	ds_read_b128 v[128:131], v179 offset:224
	ds_read_b128 v[132:135], v179 offset:192
	ds_read_b128 v[136:139], v179 offset:160
	ds_read_b128 v[140:143], v179 offset:128
	s_waitcnt lgkmcnt(0)
	s_nop 3
	v_pk_mul_f32 v[14:15], v[14:15], v[130:131]
	v_pk_mul_f32 v[12:13], v[12:13], v[128:129]
	v_pk_mul_f32 v[10:11], v[10:11], v[134:135]
	v_pk_mul_f32 v[8:9], v[8:9], v[132:133]
	v_pk_mul_f32 v[6:7], v[6:7], v[138:139]
	v_pk_mul_f32 v[4:5], v[4:5], v[136:137]
	v_pk_mul_f32 v[2:3], v[2:3], v[142:143]
	v_pk_mul_f32 v[0:1], v[0:1], v[140:141]
	v_pk_mul_f32 v[62:63], v[62:63], v[130:131]
	v_pk_mul_f32 v[60:61], v[60:61], v[128:129]
	v_pk_mul_f32 v[58:59], v[58:59], v[134:135]
	v_pk_mul_f32 v[56:57], v[56:57], v[132:133]
	v_pk_mul_f32 v[54:55], v[54:55], v[138:139]
	v_pk_mul_f32 v[52:53], v[52:53], v[136:137]
	v_pk_mul_f32 v[50:51], v[50:51], v[142:143]
	v_pk_mul_f32 v[48:49], v[48:49], v[140:141]
	v_pk_mul_f32 v[46:47], v[46:47], v[130:131]
	v_pk_mul_f32 v[44:45], v[44:45], v[128:129]
	v_pk_mul_f32 v[42:43], v[42:43], v[134:135]
	v_pk_mul_f32 v[40:41], v[40:41], v[132:133]
	v_pk_mul_f32 v[38:39], v[38:39], v[138:139]
	v_pk_mul_f32 v[36:37], v[36:37], v[136:137]
	v_pk_mul_f32 v[34:35], v[34:35], v[142:143]
	v_pk_mul_f32 v[32:33], v[32:33], v[140:141]
	v_pk_mul_f32 v[30:31], v[30:31], v[130:131]
	v_pk_mul_f32 v[28:29], v[28:29], v[128:129]
	v_pk_mul_f32 v[26:27], v[26:27], v[134:135]
	v_pk_mul_f32 v[24:25], v[24:25], v[132:133]
	v_pk_mul_f32 v[22:23], v[22:23], v[138:139]
	v_pk_mul_f32 v[20:21], v[20:21], v[136:137]
	v_pk_mul_f32 v[18:19], v[18:19], v[142:143]
	v_pk_mul_f32 v[16:17], v[16:17], v[140:141]
.Lmb_nr_h2:
	v_exp_f32_e32 v144, v144
	v_exp_f32_e32 v145, v145
	v_exp_f32_e32 v146, v146
	v_exp_f32_e32 v147, v147
	v_exp_f32_e32 v148, v148
	v_exp_f32_e32 v149, v149
	v_exp_f32_e32 v150, v150
	v_exp_f32_e32 v151, v151
	v_exp_f32_e32 v152, v152
	v_exp_f32_e32 v153, v153
	v_exp_f32_e32 v154, v154
	v_exp_f32_e32 v155, v155
	v_exp_f32_e32 v156, v156
	v_exp_f32_e32 v157, v157
	v_exp_f32_e32 v158, v158
	v_exp_f32_e32 v159, v159
	s_waitcnt lgkmcnt(0)
	s_barrier
	s_mov_b64 s[4:5], 0x180000
	v_lshl_add_u64 v[182:183], v[182:183], 0, s[4:5]
	s_addk_i32 s6, 0x80
	v_add_u32_e32 v223, 0x200, v223
	s_and_b64 vcc, exec, s[26:27]
	s_cbranch_vccz .Lmb_loop
	s_mov_b32 s28, 0
	v_mov_b32_e32 v249, v181
	s_cmpk_lt_i32 s6, 0xfd93
	s_cbranch_scc1 .Lmb_cls_pe
	v_mov_b32_e32 v249, v217
	s_cmpk_gt_i32 s6, 0x24d
	s_cbranch_scc1 .Lmb_cls_pe
	s_mov_b32 s28, 1
	v_mov_b32_e32 v249, 0

; #define LAS __attribute__((address_space(3)))
; #define SBAR() __builtin_amdgcn_sched_barrier(0)
; __device__ __forceinline__ float half_max(float v) { auto rr = __builtin_amdgcn_permlane32_swap(__float_as_uint(v), __float_as_uint(v), false, false); return fmaxf(__uint_as_float(rr[0]), __uint_as_float(rr[1])); }
; #define RESC(a) do { if (__any((a) < 1.f)) { if (hi == 0) al_l[r32] = (a); LDS_WAIT(); \
;     _Pragma("unroll") for (int r = 0; r < 16; ++r) { const float av = al_l[crow(r, hi)]; _Pragma("unroll") for (int d = 0; d < 4; ++d) o[d][r] *= av; } } } while (0)
; __device__ __forceinline__ void partialSM(f32x16& p0, f32x16& p1, const LAS float* tbp, int relc, float cL, float cR, float& m_reg, float& mn, float& alpha) {
;     float cb = 0.f;
;     if (relc + 63 <= -559) cb = cL;
;     else if (relc - 31 >= 559) cb = cR;
;     else {
; #pragma unroll
;         for (int r = 0; r < 16; ++r) { p0[r] += tbp[(r & 3) + 8 * (r >> 2)]; p1[r] += tbp[32 + (r & 3) + 8 * (r >> 2)]; }
;     }
;     float pmax = p0[0];
; #pragma unroll
;     for (int r = 1; r < 16; ++r) pmax = fmaxf(pmax, p0[r]);
; #pragma unroll
;     for (int r = 0; r < 16; ++r) pmax = fmaxf(pmax, p1[r]);
;     pmax = half_max(pmax) + cb;
;     if (__builtin_expect(__all(pmax - m_reg <= 8.f), 1)) { mn = m_reg; alpha = 1.f; }
;     else { mn = fmaxf(m_reg, pmax); alpha = __builtin_amdgcn_exp2f(m_reg - mn); m_reg = mn; }
;     const float sh = mn - cb;
; #pragma unroll
;     for (int r = 0; r < 16; ++r) { p0[r] -= sh; p1[r] -= sh; }
; #pragma unroll
;     for (int r = 0; r < 16; ++r) p0[r] = __builtin_amdgcn_exp2f(p0[r]);
; }
; __device__ __forceinline__ void unit(LAS unsigned char* lds, const bf16* __restrict__ PROJ, bf16* __restrict__ MIXED, const float* __restrict__ subln_g, float lam, int R0, int seq, int h, int qb) {
;     ...
;     SBAR(); qkt(pB0, pB1, K_lds + SHM_K, qr, r32, cb0);
;     finishSM(pA0, pA1, alA, l_reg, pa0, pa1, pa2, pa3); SBAR();
;     pv_d0(o, vb0, pa0, pa1, pa2, pa3); partialSM(pB0, pB1, tbq + (NT - 1) * 64, rc0 + (NT - 1) * 64, cL, cR, m_reg, mnB, alB);
;     __syncthreads(); RESC(alB);
.Lmb_qkj_pe:
	s_cmp_eq_u32 s28, 1
	s_cbranch_scc0 .Lmb_pv_pe
	ds_read2_b32 v[240:241], v223 offset1:1
	ds_read2_b32 v[242:243], v223 offset0:2 offset1:3
	ds_read2_b32 v[244:245], v223 offset0:8 offset1:9
	ds_read2_b32 v[246:247], v223 offset0:10 offset1:11
	ds_read2_b32 v[152:153], v223 offset0:16 offset1:17
	ds_read2_b32 v[154:155], v223 offset0:18 offset1:19
	ds_read2_b32 v[156:157], v223 offset0:24 offset1:25
	ds_read2_b32 v[158:159], v223 offset0:26 offset1:27
	s_waitcnt lgkmcnt(0)
	v_pk_add_f32 v[80:81], v[80:81], v[240:241]
	v_pk_add_f32 v[82:83], v[82:83], v[242:243]
	v_pk_add_f32 v[84:85], v[84:85], v[244:245]
	v_pk_add_f32 v[86:87], v[86:87], v[246:247]
	v_pk_add_f32 v[88:89], v[88:89], v[152:153]
	v_pk_add_f32 v[90:91], v[90:91], v[154:155]
	v_pk_add_f32 v[92:93], v[92:93], v[156:157]
	v_pk_add_f32 v[94:95], v[94:95], v[158:159]
	ds_read2_b32 v[240:241], v223 offset0:32 offset1:33
	ds_read2_b32 v[242:243], v223 offset0:34 offset1:35
	ds_read2_b32 v[244:245], v223 offset0:40 offset1:41
	ds_read2_b32 v[246:247], v223 offset0:42 offset1:43
	ds_read2_b32 v[152:153], v223 offset0:48 offset1:49
	ds_read2_b32 v[154:155], v223 offset0:50 offset1:51
	ds_read2_b32 v[156:157], v223 offset0:56 offset1:57
	ds_read2_b32 v[158:159], v223 offset0:58 offset1:59
	s_waitcnt lgkmcnt(0)
	v_pk_add_f32 v[64:65], v[64:65], v[240:241]
	v_pk_add_f32 v[66:67], v[66:67], v[242:243]
	v_pk_add_f32 v[68:69], v[68:69], v[244:245]
	v_pk_add_f32 v[70:71], v[70:71], v[246:247]
	v_pk_add_f32 v[72:73], v[72:73], v[152:153]
	v_pk_add_f32 v[74:75], v[74:75], v[154:155]
	v_pk_add_f32 v[76:77], v[76:77], v[156:157]
	v_pk_add_f32 v[78:79], v[78:79], v[158:159]
	ds_read_b64_tr_b16 v[240:241], v175 offset:0
	ds_read_b64_tr_b16 v[242:243], v175 offset:2048
	ds_read_b64_tr_b16 v[244:245], v175 offset:4096
	ds_read_b64_tr_b16 v[246:247], v175 offset:6144
	ds_read_b64_tr_b16 v[152:153], v175 offset:8192
	ds_read_b64_tr_b16 v[154:155], v175 offset:10240
	ds_read_b64_tr_b16 v[156:157], v175 offset:12288
	ds_read_b64_tr_b16 v[158:159], v175 offset:14336
.Lmb_pv_pe:
	s_nop 5
	s_waitcnt lgkmcnt(0)
	v_mfma_f32_32x32x16_bf16 v[0:15], v[232:235], v[240:243], v[0:15]
	ds_read_b64_tr_b16 v[240:241], v175 offset:512
	ds_read_b64_tr_b16 v[242:243], v175 offset:2560
	v_max3_f32 v254, v80, v81, v82
	v_max3_f32 v255, v83, v84, v85
	v_max3_f32 v254, v254, v86, v87
	v_max3_f32 v255, v255, v88, v89
	v_max3_f32 v254, v254, v90, v91
	v_max3_f32 v255, v255, v92, v93
	v_mfma_f32_32x32x16_bf16 v[0:15], v[236:239], v[244:247], v[0:15]
	ds_read_b64_tr_b16 v[244:245], v175 offset:4608
	ds_read_b64_tr_b16 v[246:247], v175 offset:6656
	v_max3_f32 v254, v254, v94, v95
	v_max3_f32 v255, v255, v64, v65
	v_max3_f32 v254, v254, v66, v67
	v_max3_f32 v255, v255, v68, v69
	v_max3_f32 v254, v254, v70, v71
	v_max3_f32 v255, v255, v72, v73
	v_mfma_f32_32x32x16_bf16 v[0:15], v[144:147], v[152:155], v[0:15]
	ds_read_b64_tr_b16 v[152:153], v175 offset:8704
	ds_read_b64_tr_b16 v[154:155], v175 offset:10752
	v_max3_f32 v254, v254, v74, v75
	v_max3_f32 v255, v255, v76, v77
	v_max3_f32 v254, v254, v78, v79
	v_max_f32_e32 v254, v254, v255
	v_mov_b32_e32 v255, v254
	v_mfma_f32_32x32x16_bf16 v[0:15], v[148:151], v[156:159], v[0:15]
	ds_read_b64_tr_b16 v[156:157], v175 offset:12800
	ds_read_b64_tr_b16 v[158:159], v175 offset:14848
	v_permlane32_swap_b32_e32 v254, v255
	v_max_f32_e32 v254, v254, v255
	v_add_f32_e32 v254, v249, v254
	v_sub_f32_e32 v255, v254, v250
	v_cmp_ge_f32_e32 vcc, s35, v255
	v_max_f32_e32 v255, v250, v254
	s_waitcnt lgkmcnt(0)
	v_mfma_f32_32x32x16_bf16 v[48:63], v[232:235], v[240:243], v[48:63]
	ds_read_b64_tr_b16 v[240:241], v175 offset:1024
	ds_read_b64_tr_b16 v[242:243], v175 offset:3072
	v_sub_f32_e32 v248, v250, v255
	v_exp_f32_e32 v248, v248
	v_sub_f32_e32 v252, v255, v249
	v_sub_f32_e32 v254, v250, v249
	s_cmp_eq_u64 vcc, exec
	s_cselect_b64 s[4:5], -1, 0
	v_cndmask_b32_e64 v251, v248, 1.0, s[4:5]
	v_mfma_f32_32x32x16_bf16 v[48:63], v[236:239], v[244:247], v[48:63]
	ds_read_b64_tr_b16 v[244:245], v175 offset:5120
	ds_read_b64_tr_b16 v[246:247], v175 offset:7168
	v_cndmask_b32_e64 v250, v255, v250, s[4:5]
	v_cndmask_b32_e64 v252, v252, v254, s[4:5]
	v_sub_f32_e32 v80, v80, v252
	v_sub_f32_e32 v81, v81, v252
	v_sub_f32_e32 v82, v82, v252
	v_sub_f32_e32 v83, v83, v252
	v_mfma_f32_32x32x16_bf16 v[48:63], v[144:147], v[152:155], v[48:63]
	ds_read_b64_tr_b16 v[152:153], v175 offset:9216
	ds_read_b64_tr_b16 v[154:155], v175 offset:11264
	v_sub_f32_e32 v84, v84, v252
	v_sub_f32_e32 v85, v85, v252
	v_sub_f32_e32 v86, v86, v252
	v_sub_f32_e32 v87, v87, v252
	v_sub_f32_e32 v88, v88, v252
	v_sub_f32_e32 v89, v89, v252
	v_mfma_f32_32x32x16_bf16 v[48:63], v[148:151], v[156:159], v[48:63]
	ds_read_b64_tr_b16 v[156:157], v175 offset:13312
	ds_read_b64_tr_b16 v[158:159], v175 offset:15360
	v_sub_f32_e32 v90, v90, v252
	v_sub_f32_e32 v91, v91, v252
	v_sub_f32_e32 v92, v92, v252
	v_sub_f32_e32 v93, v93, v252
	v_sub_f32_e32 v94, v94, v252
	v_sub_f32_e32 v95, v95, v252
	s_waitcnt lgkmcnt(0)
	v_mfma_f32_32x32x16_bf16 v[32:47], v[232:235], v[240:243], v[32:47]
	ds_read_b64_tr_b16 v[240:241], v175 offset:1536
	ds_read_b64_tr_b16 v[242:243], v175 offset:3584
	v_exp_f32_e32 v80, v80
	v_sub_f32_e32 v64, v64, v252
	v_exp_f32_e32 v81, v81
	v_sub_f32_e32 v65, v65, v252
	v_mfma_f32_32x32x16_bf16 v[32:47], v[236:239], v[244:247], v[32:47]
	ds_read_b64_tr_b16 v[244:245], v175 offset:5632
	ds_read_b64_tr_b16 v[246:247], v175 offset:7680
	v_exp_f32_e32 v82, v82
	v_sub_f32_e32 v66, v66, v252
	v_exp_f32_e32 v83, v83
	v_sub_f32_e32 v67, v67, v252
	v_mfma_f32_32x32x16_bf16 v[32:47], v[144:147], v[152:155], v[32:47]
	ds_read_b64_tr_b16 v[152:153], v175 offset:9728
	ds_read_b64_tr_b16 v[154:155], v175 offset:11776
	v_exp_f32_e32 v84, v84
	v_sub_f32_e32 v68, v68, v252
	v_exp_f32_e32 v85, v85
	v_sub_f32_e32 v69, v69, v252
	v_mfma_f32_32x32x16_bf16 v[32:47], v[148:151], v[156:159], v[32:47]
	ds_read_b64_tr_b16 v[156:157], v175 offset:13824
	ds_read_b64_tr_b16 v[158:159], v175 offset:15872
	v_exp_f32_e32 v86, v86
	v_sub_f32_e32 v70, v70, v252
	v_exp_f32_e32 v87, v87
	v_sub_f32_e32 v71, v71, v252
	s_waitcnt lgkmcnt(0)
	v_mfma_f32_32x32x16_bf16 v[16:31], v[232:235], v[240:243], v[16:31]
	v_exp_f32_e32 v88, v88
	v_sub_f32_e32 v72, v72, v252
	v_exp_f32_e32 v89, v89
	v_sub_f32_e32 v73, v73, v252
	v_mfma_f32_32x32x16_bf16 v[16:31], v[236:239], v[244:247], v[16:31]
	v_exp_f32_e32 v90, v90
	v_sub_f32_e32 v74, v74, v252
	v_exp_f32_e32 v91, v91
	v_sub_f32_e32 v75, v75, v252
	v_mfma_f32_32x32x16_bf16 v[16:31], v[144:147], v[152:155], v[16:31]
	v_exp_f32_e32 v92, v92
	v_sub_f32_e32 v76, v76, v252
	v_exp_f32_e32 v93, v93
	v_sub_f32_e32 v77, v77, v252
	v_mfma_f32_32x32x16_bf16 v[16:31], v[148:151], v[156:159], v[16:31]
	v_exp_f32_e32 v94, v94
	v_sub_f32_e32 v78, v78, v252
	v_exp_f32_e32 v95, v95
	v_sub_f32_e32 v79, v79, v252
	s_and_b64 vcc, exec, s[4:5]
	s_cbranch_vccnz .Lmb_nr_pe
; #define LAS __attribute__((address_space(3)))
; __device__ __forceinline__ void finishSM(f32x16& p0, f32x16& p1, float alpha, float& l_reg, bf16x8& pa0, bf16x8& pa1, bf16x8& pa2, bf16x8& pa3) {
; #pragma unroll
;     for (int r = 0; r < 16; ++r) p1[r] = __builtin_amdgcn_exp2f(p1[r]);
;     float ps = 0;
; #pragma unroll
;     for (int r = 0; r < 16; ++r) ps += p0[r];
; #pragma unroll
;     for (int r = 0; r < 16; ++r) ps += p1[r];
;     ps = half_add(ps);
;     l_reg = l_reg * alpha + ps;
;     PK4(p0, 0, pa0); PK4(p0, 8, pa1); PK4(p1, 0, pa2); PK4(p1, 8, pa3);
; }
; __device__ __forceinline__ void qkt(f32x16& p0, f32x16& p1, const LAS unsigned char* Ks, const bf16x8* qr, int r32, int cb0) {
; #pragma unroll
;     for (int i = 0; i < 16; ++i) { p0[i] = 0.f; p1[i] = 0.f; }
; #pragma unroll
;     for (int d0 = 0; d0 < 4; ++d0) { const int cb = cb0 + d0 * 32;
;         const bf16x8 b0 = *(const LAS bf16x8*)(Ks + KSWZ(r32, cb));
;         const bf16x8 b1 = *(const LAS bf16x8*)(Ks + KSWZ(32 + r32, cb));
;         p0 = __builtin_amdgcn_mfma_f32_32x32x16_bf16(b0, qr[d0], p0, 0, 0, 0);
;         p1 = __builtin_amdgcn_mfma_f32_32x32x16_bf16(b1, qr[d0], p1, 0, 0, 0); }
; }
; template <int D0> __device__ __forceinline__ void pv_one(f32x16& od, int vb, bf16x8 pa0, bf16x8 pa1, bf16x8 pa2, bf16x8 pa3) {
;     s16x4 l0 = tr_read<v_rd_off(D0, 0, 0)>(vb), h0 = tr_read<v_rd_off(D0, 0, 1)>(vb), l1 = tr_read<v_rd_off(D0, 1, 0)>(vb), h1 = tr_read<v_rd_off(D0, 1, 1)>(vb);
;     s16x4 l2 = tr_read<v_rd_off(D0, 2, 0)>(vb), h2 = tr_read<v_rd_off(D0, 2, 1)>(vb), l3 = tr_read<v_rd_off(D0, 3, 0)>(vb), h3 = tr_read<v_rd_off(D0, 3, 1)>(vb);
;     asm volatile("s_waitcnt lgkmcnt(0)" : "+v"(l0), "+v"(h0), "+v"(l1), "+v"(h1), "+v"(l2), "+v"(h2), "+v"(l3), "+v"(h3) :: "memory");
;     od = __builtin_amdgcn_mfma_f32_32x32x16_bf16(pa0, PKV(l0, h0), od, 0, 0, 0);
;     od = __builtin_amdgcn_mfma_f32_32x32x16_bf16(pa1, PKV(l1, h1), od, 0, 0, 0);
;     od = __builtin_amdgcn_mfma_f32_32x32x16_bf16(pa2, PKV(l2, h2), od, 0, 0, 0);
;     od = __builtin_amdgcn_mfma_f32_32x32x16_bf16(pa3, PKV(l3, h3), od, 0, 0, 0);
; }
; __device__ __forceinline__ void pv_d0(f32x16* o, int vb, bf16x8 pa0, bf16x8 pa1, bf16x8 pa2, bf16x8 pa3) {
;     pv_one<0>(o[0], vb, pa0, pa1, pa2, pa3); pv_one<1>(o[1], vb, pa0, pa1, pa2, pa3); pv_one<2>(o[2], vb, pa0, pa1, pa2, pa3); pv_one<3>(o[3], vb, pa0, pa1, pa2, pa3);
; }
	s_and_saveexec_b64 s[28:29], s[0:1]
	ds_write_b32 v215, v251 offset:128
	s_or_b64 exec, exec, s[28:29]
	s_waitcnt lgkmcnt(0)
	ds_read_b128 v[112:115], v179 offset:224
	ds_read_b128 v[116:119], v179 offset:192
	ds_read_b128 v[120:123], v179 offset:160
	ds_read_b128 v[124:127], v179 offset:128
	s_waitcnt lgkmcnt(0)
	s_nop 3
	v_pk_mul_f32 v[14:15], v[14:15], v[114:115]
	v_pk_mul_f32 v[12:13], v[12:13], v[112:113]
	v_pk_mul_f32 v[10:11], v[10:11], v[118:119]
	v_pk_mul_f32 v[8:9], v[8:9], v[116:117]
	v_pk_mul_f32 v[6:7], v[6:7], v[122:123]
	v_pk_mul_f32 v[4:5], v[4:5], v[120:121]
	v_pk_mul_f32 v[2:3], v[2:3], v[126:127]
	v_pk_mul_f32 v[0:1], v[0:1], v[124:125]
	v_pk_mul_f32 v[62:63], v[62:63], v[114:115]
	v_pk_mul_f32 v[60:61], v[60:61], v[112:113]
	v_pk_mul_f32 v[58:59], v[58:59], v[118:119]
	v_pk_mul_f32 v[56:57], v[56:57], v[116:117]
	v_pk_mul_f32 v[54:55], v[54:55], v[122:123]
	v_pk_mul_f32 v[52:53], v[52:53], v[120:121]
	v_pk_mul_f32 v[50:51], v[50:51], v[126:127]
	v_pk_mul_f32 v[48:49], v[48:49], v[124:125]
	v_pk_mul_f32 v[46:47], v[46:47], v[114:115]
	v_pk_mul_f32 v[44:45], v[44:45], v[112:113]
	v_pk_mul_f32 v[42:43], v[42:43], v[118:119]
	v_pk_mul_f32 v[40:41], v[40:41], v[116:117]
	v_pk_mul_f32 v[38:39], v[38:39], v[122:123]
	v_pk_mul_f32 v[36:37], v[36:37], v[120:121]
	v_pk_mul_f32 v[34:35], v[34:35], v[126:127]
	v_pk_mul_f32 v[32:33], v[32:33], v[124:125]
	v_pk_mul_f32 v[30:31], v[30:31], v[114:115]
	v_pk_mul_f32 v[28:29], v[28:29], v[112:113]
	v_pk_mul_f32 v[26:27], v[26:27], v[118:119]
	v_pk_mul_f32 v[24:25], v[24:25], v[116:117]
	v_pk_mul_f32 v[22:23], v[22:23], v[122:123]
	v_pk_mul_f32 v[20:21], v[20:21], v[120:121]
	v_pk_mul_f32 v[18:19], v[18:19], v[126:127]
	v_pk_mul_f32 v[16:17], v[16:17], v[124:125]
.Lmb_nr_pe:
	v_exp_f32_e32 v64, v64
	v_exp_f32_e32 v65, v65
	v_exp_f32_e32 v66, v66
	v_exp_f32_e32 v67, v67
	v_exp_f32_e32 v68, v68
	v_exp_f32_e32 v69, v69
	v_exp_f32_e32 v70, v70
	v_exp_f32_e32 v71, v71
	v_exp_f32_e32 v72, v72
	v_exp_f32_e32 v73, v73
	v_exp_f32_e32 v74, v74
	v_exp_f32_e32 v75, v75
	v_exp_f32_e32 v76, v76
	v_exp_f32_e32 v77, v77
	v_exp_f32_e32 v78, v78
	v_exp_f32_e32 v79, v79
	v_add_f32_e32 v254, v80, v81
	v_add_f32_e32 v255, v82, v83
	v_add_f32_e32 v254, v254, v84
	v_add_f32_e32 v255, v255, v85
	v_add_f32_e32 v254, v254, v86
	v_add_f32_e32 v255, v255, v87
	v_add_f32_e32 v254, v254, v88
	v_add_f32_e32 v255, v255, v89
	v_add_f32_e32 v254, v254, v90
	v_add_f32_e32 v255, v255, v91
	v_add_f32_e32 v254, v254, v92
	v_add_f32_e32 v255, v255, v93
	v_add_f32_e32 v254, v254, v94
	v_add_f32_e32 v255, v255, v95
	v_add_f32_e32 v254, v254, v64
	v_add_f32_e32 v255, v255, v65
	v_add_f32_e32 v254, v254, v66
	v_add_f32_e32 v255, v255, v67
	v_add_f32_e32 v254, v254, v68
	v_add_f32_e32 v255, v255, v69
	v_add_f32_e32 v254, v254, v70
	v_add_f32_e32 v255, v255, v71
	v_add_f32_e32 v254, v254, v72
	v_add_f32_e32 v255, v255, v73
	v_add_f32_e32 v254, v254, v74
	v_add_f32_e32 v255, v255, v75
	v_add_f32_e32 v254, v254, v76
	v_add_f32_e32 v255, v255, v77
	v_add_f32_e32 v254, v254, v78
	v_add_f32_e32 v255, v255, v79
	v_add_f32_e32 v254, v254, v255
	v_mov_b32_e32 v255, v254
	v_cvt_pk_bf16_f32 v80, v80, v81
	v_cvt_pk_bf16_f32 v81, v82, v83
	v_cvt_pk_bf16_f32 v82, v84, v85
	v_cvt_pk_bf16_f32 v83, v86, v87
	v_cvt_pk_bf16_f32 v84, v88, v89
	v_cvt_pk_bf16_f32 v85, v90, v91
	v_cvt_pk_bf16_f32 v86, v92, v93
	v_cvt_pk_bf16_f32 v87, v94, v95
	v_permlane32_swap_b32_e32 v254, v255
	v_cvt_pk_bf16_f32 v64, v64, v65
	v_cvt_pk_bf16_f32 v65, v66, v67
	v_cvt_pk_bf16_f32 v66, v68, v69
	v_cvt_pk_bf16_f32 v67, v70, v71
	v_cvt_pk_bf16_f32 v68, v72, v73
	v_cvt_pk_bf16_f32 v69, v74, v75
	v_cvt_pk_bf16_f32 v70, v76, v77
	v_cvt_pk_bf16_f32 v71, v78, v79
	v_add_f32_e32 v254, v254, v255
	v_fma_f32 v216, v216, v251, v254
	v_permlane32_swap_b32_e32 v80, v82
	v_permlane32_swap_b32_e32 v81, v83
	v_permlane32_swap_b32_e32 v84, v86
	v_permlane32_swap_b32_e32 v85, v87
	v_permlane32_swap_b32_e32 v64, v66
	v_permlane32_swap_b32_e32 v65, v67
	v_permlane32_swap_b32_e32 v68, v70
	v_permlane32_swap_b32_e32 v69, v71
	ds_read_b64_tr_b16 v[88:89], v186 offset:0
	ds_read_b64_tr_b16 v[90:91], v186 offset:2048
	ds_read_b64_tr_b16 v[92:93], v186 offset:4096
	ds_read_b64_tr_b16 v[94:95], v186 offset:6144
	ds_read_b64_tr_b16 v[72:73], v186 offset:8192
	ds_read_b64_tr_b16 v[74:75], v186 offset:10240
	ds_read_b64_tr_b16 v[76:77], v186 offset:12288
	ds_read_b64_tr_b16 v[78:79], v186 offset:14336
	s_waitcnt lgkmcnt(0)
	v_mfma_f32_32x32x16_bf16 v[0:15], v[80:83], v[88:91], v[0:15]
	ds_read_b64_tr_b16 v[88:89], v186 offset:512
	ds_read_b64_tr_b16 v[90:91], v186 offset:2560
	v_mfma_f32_32x32x16_bf16 v[0:15], v[84:87], v[92:95], v[0:15]
	ds_read_b64_tr_b16 v[92:93], v186 offset:4608
	ds_read_b64_tr_b16 v[94:95], v186 offset:6656
	v_mfma_f32_32x32x16_bf16 v[0:15], v[64:67], v[72:75], v[0:15]
	ds_read_b64_tr_b16 v[72:73], v186 offset:8704
	ds_read_b64_tr_b16 v[74:75], v186 offset:10752
	v_mfma_f32_32x32x16_bf16 v[0:15], v[68:71], v[76:79], v[0:15]
	ds_read_b64_tr_b16 v[76:77], v186 offset:12800
	ds_read_b64_tr_b16 v[78:79], v186 offset:14848
	s_waitcnt lgkmcnt(0)
	v_mfma_f32_32x32x16_bf16 v[48:63], v[80:83], v[88:91], v[48:63]
	ds_read_b64_tr_b16 v[88:89], v186 offset:1024
	ds_read_b64_tr_b16 v[90:91], v186 offset:3072
	v_mfma_f32_32x32x16_bf16 v[48:63], v[84:87], v[92:95], v[48:63]
	ds_read_b64_tr_b16 v[92:93], v186 offset:5120
	ds_read_b64_tr_b16 v[94:95], v186 offset:7168
	v_mfma_f32_32x32x16_bf16 v[48:63], v[64:67], v[72:75], v[48:63]
	ds_read_b64_tr_b16 v[72:73], v186 offset:9216
	ds_read_b64_tr_b16 v[74:75], v186 offset:11264
	v_mfma_f32_32x32x16_bf16 v[48:63], v[68:71], v[76:79], v[48:63]
	ds_read_b64_tr_b16 v[76:77], v186 offset:13312
	ds_read_b64_tr_b16 v[78:79], v186 offset:15360
	s_waitcnt lgkmcnt(0)
; #define LAS __attribute__((address_space(3)))
; #define LDS_WAIT() asm volatile("s_waitcnt lgkmcnt(0)" ::: "memory")
; __device__ __forceinline__ int crow(int r, int hi) { return (r & 3) + 8 * (r >> 2) + 4 * hi; }
; __device__ __forceinline__ void unit(LAS unsigned char* lds, const bf16* __restrict__ PROJ, bf16* __restrict__ MIXED, const float* __restrict__ subln_g, float lam, int R0, int seq, int h, int qb) {
;     ...
;     pv_d0(o, vb0 + SHM_V, pa0, pa1, pa2, pa3);
;     ...
;     if (hi == 0) li_l[r32] = l_reg; LDS_WAIT();
;     float rli[16];
; #pragma unroll
;     for (int r = 0; r < 16; ++r) rli[r] = __builtin_amdgcn_rcpf(li_l[crow(r, hi)]);
;     __syncthreads();
;     LAS float* xch = (LAS float*)lds + g * 4096;
;     if (c == 1) {
; #pragma unroll
;         for (int d = 0; d < 4; ++d)
; #pragma unroll
;             for (int r = 0; r < 16; ++r) xch[(d * 16 + r) * 64 + lane] = o[d][r] * rli[r]; }
	v_mfma_f32_32x32x16_bf16 v[32:47], v[80:83], v[88:91], v[32:47]
	ds_read_b64_tr_b16 v[88:89], v186 offset:1536
	ds_read_b64_tr_b16 v[90:91], v186 offset:3584
	v_mfma_f32_32x32x16_bf16 v[32:47], v[84:87], v[92:95], v[32:47]
	ds_read_b64_tr_b16 v[92:93], v186 offset:5632
	ds_read_b64_tr_b16 v[94:95], v186 offset:7680
	v_mfma_f32_32x32x16_bf16 v[32:47], v[64:67], v[72:75], v[32:47]
	ds_read_b64_tr_b16 v[72:73], v186 offset:9728
	ds_read_b64_tr_b16 v[74:75], v186 offset:11776
	v_mfma_f32_32x32x16_bf16 v[32:47], v[68:71], v[76:79], v[32:47]
	ds_read_b64_tr_b16 v[76:77], v186 offset:13824
	ds_read_b64_tr_b16 v[78:79], v186 offset:15872
	s_waitcnt lgkmcnt(0)
	v_mfma_f32_32x32x16_bf16 v[16:31], v[80:83], v[88:91], v[16:31]
	v_mfma_f32_32x32x16_bf16 v[16:31], v[84:87], v[92:95], v[16:31]
	v_mfma_f32_32x32x16_bf16 v[16:31], v[64:67], v[72:75], v[16:31]
	v_mfma_f32_32x32x16_bf16 v[16:31], v[68:71], v[76:79], v[16:31]
	s_and_saveexec_b64 s[4:5], s[0:1]
	ds_write_b32 v215, v216
	s_or_b64 exec, exec, s[4:5]
	s_waitcnt lgkmcnt(0)
	ds_read_b128 v[64:67], v179
	ds_read_b128 v[68:71], v179 offset:32
	s_lshl_b32 s4, s95, 14
	s_add_i32 s6, s4, 0
	s_cmp_eq_u32 s71, 0
	s_waitcnt lgkmcnt(1)
	v_rcp_f32_e32 v80, v64
	v_rcp_f32_e32 v79, v65
	v_rcp_f32_e32 v78, v66
	v_rcp_f32_e32 v102, v67
	s_waitcnt lgkmcnt(0)
	v_rcp_f32_e32 v107, v68
	ds_read_b128 v[64:67], v179 offset:64
	v_rcp_f32_e32 v106, v69
	v_rcp_f32_e32 v105, v70
	v_rcp_f32_e32 v104, v71
	ds_read_b128 v[68:71], v179 offset:96
	s_waitcnt lgkmcnt(1)
	v_rcp_f32_e32 v97, v64
	v_rcp_f32_e32 v96, v65
	v_rcp_f32_e32 v95, v66
	v_rcp_f32_e32 v94, v67
	s_waitcnt lgkmcnt(0)
	v_rcp_f32_e32 v93, v68
	v_rcp_f32_e32 v92, v69
	v_rcp_f32_e32 v91, v70
	v_rcp_f32_e32 v90, v71
	s_cselect_b64 s[4:5], -1, 0
	s_and_b64 vcc, exec, s[4:5]
	v_lshl_add_u32 v98, v190, 2, s6
	s_barrier
	s_cbranch_vccnz .LBB0_294
	v_mul_f32_e32 v64, v0, v80
	v_mul_f32_e32 v65, v1, v79
	ds_write2st64_b32 v98, v64, v65 offset1:1
	v_mul_f32_e32 v64, v2, v78
	v_mul_f32_e32 v65, v3, v102
	ds_write2st64_b32 v98, v64, v65 offset0:2 offset1:3
	v_mul_f32_e32 v64, v4, v107
	v_mul_f32_e32 v65, v5, v106
	ds_write2st64_b32 v98, v64, v65 offset0:4 offset1:5
	v_mul_f32_e32 v64, v6, v105
	v_mul_f32_e32 v65, v7, v104
	ds_write2st64_b32 v98, v64, v65 offset0:6 offset1:7
	v_mul_f32_e32 v64, v8, v97
	v_mul_f32_e32 v65, v9, v96
	ds_write2st64_b32 v98, v64, v65 offset0:8 offset1:9
	v_mul_f32_e32 v64, v10, v95
	v_mul_f32_e32 v65, v11, v94
	ds_write2st64_b32 v98, v64, v65 offset0:10 offset1:11
	v_mul_f32_e32 v64, v12, v93
	v_mul_f32_e32 v65, v13, v92
	ds_write2st64_b32 v98, v64, v65 offset0:12 offset1:13
	v_mul_f32_e32 v64, v14, v91
	v_mul_f32_e32 v65, v15, v90
	ds_write2st64_b32 v98, v64, v65 offset0:14 offset1:15
	v_mul_f32_e32 v64, v48, v80
	v_mul_f32_e32 v65, v49, v79
	ds_write2st64_b32 v98, v64, v65 offset0:16 offset1:17
	v_mul_f32_e32 v64, v50, v78
	v_mul_f32_e32 v65, v51, v102
	ds_write2st64_b32 v98, v64, v65 offset0:18 offset1:19
	v_mul_f32_e32 v64, v52, v107
	v_mul_f32_e32 v65, v53, v106
	ds_write2st64_b32 v98, v64, v65 offset0:20 offset1:21
	v_mul_f32_e32 v64, v54, v105
	v_mul_f32_e32 v65, v55, v104
	ds_write2st64_b32 v98, v64, v65 offset0:22 offset1:23
	v_mul_f32_e32 v64, v56, v97
	v_mul_f32_e32 v65, v57, v96
	ds_write2st64_b32 v98, v64, v65 offset0:24 offset1:25
	v_mul_f32_e32 v64, v58, v95
	v_mul_f32_e32 v65, v59, v94
	ds_write2st64_b32 v98, v64, v65 offset0:26 offset1:27
	v_mul_f32_e32 v64, v60, v93
	v_mul_f32_e32 v65, v61, v92
	ds_write2st64_b32 v98, v64, v65 offset0:28 offset1:29
	v_mul_f32_e32 v64, v62, v91
	v_mul_f32_e32 v65, v63, v90
	ds_write2st64_b32 v98, v64, v65 offset0:30 offset1:31
	v_mul_f32_e32 v64, v32, v80
	v_mul_f32_e32 v65, v33, v79
	ds_write2st64_b32 v98, v64, v65 offset0:32 offset1:33
	v_mul_f32_e32 v64, v34, v78
	v_mul_f32_e32 v65, v35, v102
	ds_write2st64_b32 v98, v64, v65 offset0:34 offset1:35
	v_mul_f32_e32 v64, v36, v107
	v_mul_f32_e32 v65, v37, v106
	ds_write2st64_b32 v98, v64, v65 offset0:36 offset1:37
	v_mul_f32_e32 v64, v38, v105
	v_mul_f32_e32 v65, v39, v104
	ds_write2st64_b32 v98, v64, v65 offset0:38 offset1:39
	v_mul_f32_e32 v64, v40, v97
	v_mul_f32_e32 v65, v41, v96
	ds_write2st64_b32 v98, v64, v65 offset0:40 offset1:41
	v_mul_f32_e32 v64, v42, v95
	v_mul_f32_e32 v65, v43, v94
	ds_write2st64_b32 v98, v64, v65 offset0:42 offset1:43
	v_mul_f32_e32 v64, v44, v93
	v_mul_f32_e32 v65, v45, v92
	ds_write2st64_b32 v98, v64, v65 offset0:44 offset1:45
	v_mul_f32_e32 v64, v46, v91
	v_mul_f32_e32 v65, v47, v90
	ds_write2st64_b32 v98, v64, v65 offset0:46 offset1:47
	v_mul_f32_e32 v64, v16, v80
	v_mul_f32_e32 v65, v17, v79
	ds_write2st64_b32 v98, v64, v65 offset0:48 offset1:49
	v_mul_f32_e32 v64, v18, v78
	v_mul_f32_e32 v65, v19, v102
	ds_write2st64_b32 v98, v64, v65 offset0:50 offset1:51
	v_mul_f32_e32 v64, v20, v107
	v_mul_f32_e32 v65, v21, v106
	ds_write2st64_b32 v98, v64, v65 offset0:52 offset1:53
	v_mul_f32_e32 v64, v22, v105
	v_mul_f32_e32 v65, v23, v104
	ds_write2st64_b32 v98, v64, v65 offset0:54 offset1:55
	v_mul_f32_e32 v64, v24, v97
	v_mul_f32_e32 v65, v25, v96
	ds_write2st64_b32 v98, v64, v65 offset0:56 offset1:57
	v_mul_f32_e32 v64, v26, v95
	v_mul_f32_e32 v65, v27, v94
	ds_write2st64_b32 v98, v64, v65 offset0:58 offset1:59
	v_mul_f32_e32 v64, v28, v93
	v_mul_f32_e32 v65, v29, v92
	ds_write2st64_b32 v98, v64, v65 offset0:60 offset1:61
	v_mul_f32_e32 v64, v30, v91
	v_mul_f32_e32 v65, v31, v90
	ds_write2st64_b32 v98, v64, v65 offset0:62 offset1:63

; __global__ void __launch_bounds__(512, 2) fwd_mega(Args a) {
	.amdhsa_kernel _Z8fwd_mega4Args
		.amdhsa_group_segment_fixed_size 0
		.amdhsa_private_segment_fixed_size 0
		.amdhsa_kernarg_size 424
		.amdhsa_user_sgpr_count 2
		.amdhsa_user_sgpr_dispatch_ptr 0
		.amdhsa_user_sgpr_queue_ptr 0
		.amdhsa_user_sgpr_kernarg_segment_ptr 1
		.amdhsa_user_sgpr_dispatch_id 0
		.amdhsa_user_sgpr_kernarg_preload_length 0
		.amdhsa_user_sgpr_kernarg_preload_offset 0
		.amdhsa_user_sgpr_private_segment_size 0
		.amdhsa_uses_dynamic_stack 0
		.amdhsa_enable_private_segment 0
		.amdhsa_system_sgpr_workgroup_id_x 1
		.amdhsa_system_sgpr_workgroup_id_y 0
		.amdhsa_system_sgpr_workgroup_id_z 0
		.amdhsa_system_sgpr_workgroup_info 0
		.amdhsa_system_vgpr_workitem_id 2
		.amdhsa_next_free_vgpr 256
		.amdhsa_next_free_sgpr 98
		.amdhsa_accum_offset 256
		.amdhsa_reserve_vcc 1
		.amdhsa_float_round_mode_32 0
		.amdhsa_float_round_mode_16_64 0
		.amdhsa_float_denorm_mode_32 3
		.amdhsa_float_denorm_mode_16_64 3
		.amdhsa_dx10_clamp 1
		.amdhsa_ieee_mode 1
		.amdhsa_fp16_overflow 0
		.amdhsa_tg_split 0
		.amdhsa_exception_fp_ieee_invalid_op 0
		.amdhsa_exception_fp_denorm_src 0
		.amdhsa_exception_fp_ieee_div_zero 0
		.amdhsa_exception_fp_ieee_overflow 0
		.amdhsa_exception_fp_ieee_underflow 0
		.amdhsa_exception_fp_ieee_inexact 0
		.amdhsa_exception_int_div_zero 0
	.end_amdhsa_kernel

; __global__ void __launch_bounds__(512, 2) fwd_mega(Args a) {
amdhsa.kernels:
  - .agpr_count:     0
    .args:
      - .offset:         0
        .size:           168
        .value_kind:     by_value
      - .offset:         168
        .size:           4
        .value_kind:     hidden_block_count_x
      - .offset:         172
        .size:           4
        .value_kind:     hidden_block_count_y
      - .offset:         176
        .size:           4
        .value_kind:     hidden_block_count_z
      - .offset:         180
        .size:           2
        .value_kind:     hidden_group_size_x
      - .offset:         182
        .size:           2
        .value_kind:     hidden_group_size_y
      - .offset:         184
        .size:           2
        .value_kind:     hidden_group_size_z
      - .offset:         186
        .size:           2
        .value_kind:     hidden_remainder_x
      - .offset:         188
        .size:           2
        .value_kind:     hidden_remainder_y
      - .offset:         190
        .size:           2
        .value_kind:     hidden_remainder_z
      - .offset:         208
        .size:           8
        .value_kind:     hidden_global_offset_x
      - .offset:         216
        .size:           8
        .value_kind:     hidden_global_offset_y
      - .offset:         224
        .size:           8
        .value_kind:     hidden_global_offset_z
      - .offset:         232
        .size:           2
        .value_kind:     hidden_grid_dims
      - .offset:         256
        .size:           8
        .value_kind:     hidden_multigrid_sync_arg
      - .offset:         288
        .size:           4
        .value_kind:     hidden_dynamic_lds_size
    .group_segment_fixed_size: 0
    .kernarg_segment_align: 8
    .kernarg_segment_size: 424
    .language:       OpenCL C
    .language_version:
      - 2
      - 0
    .max_flat_workgroup_size: 512
    .name:           _Z8fwd_mega4Args
    .private_segment_fixed_size: 0
    .sgpr_count:     104
    .sgpr_spill_count: 30
    .symbol:         _Z8fwd_mega4Args.kd
    .uniform_work_group_size: 1
    .uses_dynamic_stack: false
    .vgpr_count:     256
    .vgpr_spill_count: 0
    .wavefront_size: 64
